# P1 row loop: 8-head forget-logit reduction as a transposing DPP reduction (32 VALU instead of 88), on cp3
# baseline (speedup 1.0000x reference)
; #define GAS __attribute__((address_space(1)))
; template <int LO, int HI> __global__ void __launch_bounds__(NWAVES * 64, 2) fox_fwd(Args args) {
;     ...
;         const int m0 = gw * 16, b = m0 / T;
;         f32x4 gm[4], sh[4];
; #pragma unroll
;         for (int j = 0; j < 4; ++j) { const int col = P1COL(j); const f32x4 g = *(const f32x4*)(norm_g + col), scl = *(const f32x4*)(ADA + b * 3072 + 1024 + col);
;             gm[j] = g * (scl + 1.0f); sh[j] = *(const f32x4*)(ADA + b * 3072 + col); }
;         const float bfv = b_f[lane & 7]; f32x4 lsq[4];
; #pragma unroll
;         for (int k = 0; k < 4; ++k) lsq[k] = (f32x4){0.f, 0.f, 0.f, 0.f};
;         for (int r = 0; r < 16; ++r) { const int m = m0 + r;
;             const GAS float* xr = (const GAS float*)(x + (size_t)m * D);
;             f32x4 v[4]; float s2 = 0.f;
; #pragma unroll
;             for (int j = 0; j < 4; ++j) { v[j] = *(const GAS f32x4*)(xr + P1COL(j)); s2 += (v[j][0] * v[j][0] + v[j][1] * v[j][1]) + (v[j][2] * v[j][2] + v[j][3] * v[j][3]); }
.LBB0_130:
	s_or_b64 exec, exec, s[8:9]
	s_ashr_i32 s43, s15, 6
	s_lshl_b32 s8, s14, 3
	s_add_i32 s33, s8, s43
	s_ashr_i32 s8, s33, 31
	s_lshr_b32 s8, s8, 24
	s_add_i32 s8, s33, s8
	s_ashr_i32 s44, s8, 8
	s_mul_i32 s8, s44, 0xc00
	s_ashr_i32 s9, s8, 31
	s_lshl_b64 s[8:9], s[8:9], 2
	s_add_u32 s8, s26, s8
	s_addc_u32 s9, s27, s9
	s_add_u32 s10, s8, 0x1000
	s_addc_u32 s11, s9, 0
	s_lshl_b32 s28, s33, 4
	s_ashr_i32 s29, s28, 31
	s_lshl_b64 s[12:13], s[28:29], 12
	v_and_b32_e32 v1, 63, v34
	s_waitcnt lgkmcnt(0)
	s_add_u32 s30, s6, s12
	v_lshlrev_b32_e32 v54, 5, v1
	s_addc_u32 s31, s7, s13
	s_barrier
	global_load_dwordx4 v[26:29], v54, s[30:31]
	global_load_dwordx4 v[18:21], v54, s[30:31] offset:16
	global_load_dwordx4 v[22:25], v54, s[30:31] offset:2064
	global_load_dwordx4 v[30:33], v54, s[30:31] offset:2048
	global_load_dwordx4 v[38:41], v54, s[10:11] offset:16
	global_load_dwordx4 v[42:45], v54, s[10:11]
	v_mbcnt_lo_u32_b32 v3, -1, 0
	v_and_b32_e32 v2, 7, v34
	v_mbcnt_hi_u32_b32 v35, -1, v3
	v_or_b32_e32 v3, 0x800, v54
	v_lshlrev_b32_e32 v2, 2, v2
	global_load_dwordx4 v[46:49], v3, s[10:11] offset:16
	global_load_dwordx4 v[50:53], v3, s[10:11]
	global_load_dwordx4 v[58:61], v54, s[20:21] offset:16
	global_load_dwordx4 v[62:65], v54, s[20:21]
	global_load_dwordx4 v[74:77], v54, s[20:21] offset:2064
	global_load_dwordx4 v[78:81], v54, s[20:21] offset:2048
	global_load_dword v71, v2, s[4:5]
	v_xor_b32_e32 v83, 16, v35
	v_and_b32_e32 v68, 64, v35
	v_mov_b32_e32 v37, 0
	v_lshlrev_b32_e32 v36, 4, v1
	v_xor_b32_e32 v4, 1, v35
	v_add_u32_e32 v87, 64, v68
	s_mov_b64 s[12:13], 0x2000000
	v_xor_b32_e32 v5, 2, v35
	v_lshl_add_u64 v[2:3], s[26:27], 0, v[36:37]
	v_cmp_lt_i32_e32 vcc, v4, v87
	v_lshl_add_u64 v[56:57], v[2:3], 0, s[12:13]
	v_xor_b32_e32 v55, 4, v35
	v_cndmask_b32_e32 v2, v35, v4, vcc
	v_cmp_lt_i32_e32 vcc, v5, v87
	v_lshlrev_b32_e32 v165, 2, v2
	v_xor_b32_e32 v73, 8, v35
	v_cndmask_b32_e32 v88, v35, v5, vcc
	global_load_dwordx4 v[2:5], v54, s[8:9] offset:16
	global_load_dwordx4 v[6:9], v54, s[8:9]
	v_lshlrev_b32_e32 v169, 2, v88
	v_cmp_lt_i32_e32 vcc, v55, v87
	v_xor_b32_e32 v86, 32, v35
	v_mov_b32_e32 v69, 0x358637bd
	v_cndmask_b32_e32 v55, v35, v55, vcc
	v_lshlrev_b32_e32 v168, 2, v55
	v_cmp_lt_i32_e32 vcc, v73, v87
	s_mov_b32 s45, 0xf800000
	v_mov_b32_e32 v70, 0x260
	v_cndmask_b32_e32 v73, v35, v73, vcc
	v_lshlrev_b32_e32 v167, 2, v73
	v_cmp_lt_i32_e32 vcc, v83, v87
	s_lshl_b64 s[34:35], s[28:29], 11
	v_add_u32_e32 v72, 0, v54
	s_or_b32 s36, s28, 1
	s_ashr_i32 s37, s36, 31
	v_cmp_eq_u32_e64 s[10:11], 4, v1
	v_cmp_eq_u32_e64 s[12:13], 5, v1
	v_cmp_eq_u32_e64 s[14:15], 6, v1
	v_cmp_eq_u32_e64 s[16:17], 7, v1
	s_mov_b32 s29, 0xbfb8aa3b
	s_mov_b32 s46, 0x7f800000
	s_mov_b32 s47, 0x33800000
	s_movk_i32 s48, 0x2000
	s_mov_b64 s[38:39], 0x2800
	s_mov_b64 s[40:41], 0x800
	s_waitcnt vmcnt(14)
	v_pk_mul_f32 v[10:11], v[28:29], v[28:29]
	v_pk_mul_f32 v[12:13], v[26:27], v[26:27]
	s_waitcnt vmcnt(13)
	v_pk_mul_f32 v[14:15], v[20:21], v[20:21]
	v_pk_mul_f32 v[16:17], v[18:19], v[18:19]
	v_pk_mov_b32 v[84:85], v[12:13], v[10:11] op_sel:[1,0]
	v_mov_b32_e32 v13, v11
	v_pk_mov_b32 v[10:11], v[16:17], v[14:15] op_sel:[1,0]
	v_mov_b32_e32 v17, v15
	s_waitcnt vmcnt(11)
	v_mul_f32_e32 v66, v31, v31
	v_mul_f32_e32 v82, v33, v33
	v_pk_add_f32 v[12:13], v[84:85], v[12:13]
	v_pk_add_f32 v[10:11], v[10:11], v[16:17]
	v_mul_f32_e32 v89, v22, v22
	v_mul_f32_e32 v90, v23, v23
	v_mul_f32_e32 v91, v24, v24
	v_mul_f32_e32 v92, v25, v25
	v_pk_fma_f32 v[14:15], v[30:31], v[30:31], v[66:67] op_sel_hi:[1,1,0]
	v_pk_fma_f32 v[66:67], v[32:33], v[32:33], v[82:83] op_sel_hi:[1,1,0]
	v_pk_add_f32 v[12:13], v[12:13], v[12:13] op_sel:[0,1] op_sel_hi:[1,0]
	v_pk_add_f32 v[10:11], v[10:11], v[10:11] op_sel:[0,1] op_sel_hi:[1,0]
	v_mov_b32_e32 v15, v91
	v_mov_b32_e32 v67, v92
	v_mov_b32_e32 v13, v89
	v_mov_b32_e32 v11, v90
	v_pk_add_f32 v[14:15], v[14:15], v[66:67]
	v_pk_add_f32 v[10:11], v[12:13], v[10:11]
	v_cndmask_b32_e32 v82, v35, v83, vcc
	v_pk_add_f32 v[10:11], v[10:11], v[14:15]
	v_lshlrev_b32_e32 v166, 2, v82
	v_add_f32_e32 v66, v10, v11
	global_load_dwordx4 v[10:13], v54, s[8:9] offset:2064
	global_load_dwordx4 v[14:17], v54, s[8:9] offset:2048
	ds_bpermute_b32 v67, v165, v66
	s_waitcnt vmcnt(12)
	v_pk_add_f32 v[82:83], v[38:39], 1.0 op_sel_hi:[1,0]
	v_cmp_lt_i32_e32 vcc, v86, v87
	s_waitcnt vmcnt(11)
	v_pk_add_f32 v[44:45], v[44:45], 1.0 op_sel_hi:[1,0]
	s_waitcnt vmcnt(9)
	v_pk_add_f32 v[52:53], v[52:53], 1.0 op_sel_hi:[1,0]
	s_waitcnt lgkmcnt(0)
	v_add_f32_e32 v66, v66, v67
	ds_bpermute_b32 v67, v169, v66
	v_pk_add_f32 v[42:43], v[42:43], 1.0 op_sel_hi:[1,0]
	v_pk_add_f32 v[50:51], v[50:51], 1.0 op_sel_hi:[1,0]
	v_pk_add_f32 v[84:85], v[48:49], 1.0 op_sel_hi:[1,0]
	s_waitcnt vmcnt(5)
	v_pk_mul_f32 v[48:49], v[78:79], v[50:51]
	s_waitcnt lgkmcnt(0)
	v_add_f32_e32 v55, v66, v67
	ds_bpermute_b32 v66, v168, v55
	v_cndmask_b32_e32 v67, v35, v86, vcc
	v_lshlrev_b32_e32 v164, 2, v67
	v_pk_add_f32 v[86:87], v[46:47], 1.0 op_sel_hi:[1,0]
	v_pk_mul_f32 v[50:51], v[76:77], v[84:85]
	s_waitcnt lgkmcnt(0)
	v_add_f32_e32 v55, v55, v66
	ds_bpermute_b32 v73, v167, v55
	v_pk_add_f32 v[66:67], v[40:41], 1.0 op_sel_hi:[1,0]
	v_pk_mul_f32 v[40:41], v[62:63], v[42:43]
	v_pk_mul_f32 v[42:43], v[60:61], v[66:67]
	v_cmp_eq_u32_e64 s[8:9], 3, v1
	s_waitcnt lgkmcnt(0)
	v_add_f32_e32 v38, v55, v73
	ds_bpermute_b32 v39, v166, v38
	s_waitcnt lgkmcnt(0)
	v_add_f32_e32 v46, v38, v39
	ds_bpermute_b32 v47, v164, v46
	v_pk_mul_f32 v[38:39], v[64:65], v[44:45]
	v_pk_mul_f32 v[44:45], v[58:59], v[82:83]
	s_waitcnt lgkmcnt(0)
; #define GAS __attribute__((address_space(1)))
; #define LAS __attribute__((address_space(3)))
; __device__ __forceinline__ unsigned pk2(float lo, float hi) { return pg8::cvt_pk_bf16(lo, hi); }
; template <int LO, int HI> __global__ void __launch_bounds__(NWAVES * 64, 2) fox_fwd(Args args) {
;     ...
;             for (int j = 0; j < 4; ++j) { v[j] = *(const GAS f32x4*)(xr + P1COL(j)); s2 += (v[j][0] * v[j][0] + v[j][1] * v[j][1]) + (v[j][2] * v[j][2] + v[j][3] * v[j][3]); }
;             const float rstd = 1.0f / sqrtf(wave_sum(s2) * (1.0f / D) + EPS);
; #pragma unroll
;             for (int j = 0; j < 4; ++j) v[j] = v[j] * rstd * gm[j] + sh[j];
; #pragma unroll
;             for (int j = 0; j < 2; ++j) { v4u o; o.x = pk2(v[2 * j][0], v[2 * j][1]); o.y = pk2(v[2 * j][2], v[2 * j][3]); o.z = pk2(v[2 * j + 1][0], v[2 * j + 1][1]); o.w = pk2(v[2 * j + 1][2], v[2 * j + 1][3]);
;                 *(GAS v4u*)(HB + (size_t)m * D + 8 * lane + 512 * j) = o; }
;             float fl[8];
; #pragma unroll
;             for (int q = 0; q < 8; ++q) { float a = 0.f;
; #pragma unroll
;                 for (int j = 0; j < 4; ++j) { const f32x4 w = *(const LAS f32x4*)(wf + q * 1024 + P1COL(j)); a += (v[j][0] * w[0] + v[j][1] * w[1]) + (v[j][2] * w[2] + v[j][3] * w[3]); }
;                 fl[q] = wave_sum(a); }
	v_add_f32_e32 v46, v46, v47
	v_fmamk_f32 v46, v46, 0x3a800000, v69
	v_mul_f32_e32 v47, 0x4f800000, v46
	v_cmp_gt_f32_e32 vcc, s45, v46
	s_nop 1
	v_cndmask_b32_e32 v55, v46, v47, vcc
	v_sqrt_f32_e32 v58, v55
	v_pk_mul_f32 v[46:47], v[80:81], v[52:53]
	v_add_u32_e32 v52, -1, v58
	v_add_u32_e32 v53, 1, v58
	v_fma_f32 v59, -v52, v58, v55
	v_fma_f32 v60, -v53, v58, v55
	v_cmp_ge_f32_e64 s[4:5], 0, v59
	s_nop 1
	v_cndmask_b32_e64 v52, v58, v52, s[4:5]
	v_cmp_lt_f32_e64 s[4:5], 0, v60
	s_nop 1
	v_cndmask_b32_e64 v52, v52, v53, s[4:5]
	v_mul_f32_e32 v53, 0x37800000, v52
	v_cndmask_b32_e32 v52, v52, v53, vcc
	v_cmp_class_f32_e32 vcc, v55, v70
	s_nop 1
	v_cndmask_b32_e32 v55, v52, v55, vcc
	v_div_scale_f32 v58, s[4:5], v55, v55, 1.0
	v_rcp_f32_e32 v59, v58
	v_div_scale_f32 v60, vcc, 1.0, v55, 1.0
	v_pk_mul_f32 v[52:53], v[74:75], v[86:87]
	v_fma_f32 v61, -v58, v59, 1.0
	v_fmac_f32_e32 v59, v61, v59
	v_mul_f32_e32 v61, v60, v59
	v_fma_f32 v62, -v58, v61, v60
	v_fmac_f32_e32 v61, v62, v59
	v_fma_f32 v58, -v58, v61, v60
	v_div_fmas_f32 v58, v58, v59, v61
	v_div_fixup_f32 v64, v58, v55, 1.0
	v_pk_mul_f32 v[18:19], v[64:65], v[18:19] op_sel_hi:[0,1]
	v_pk_mul_f32 v[20:21], v[64:65], v[20:21] op_sel_hi:[0,1]
	s_waitcnt vmcnt(3)
	v_pk_fma_f32 v[60:61], v[42:43], v[20:21], v[4:5]
	v_pk_fma_f32 v[62:63], v[44:45], v[18:19], v[2:3]
	v_pk_mul_f32 v[18:19], v[64:65], v[30:31] op_sel_hi:[0,1]
	v_pk_mul_f32 v[20:21], v[64:65], v[32:33] op_sel_hi:[0,1]
	v_pk_mul_f32 v[58:59], v[64:65], v[26:27] op_sel_hi:[0,1]
	v_pk_mul_f32 v[26:27], v[64:65], v[28:29] op_sel_hi:[0,1]
	s_waitcnt vmcnt(0)
	v_pk_fma_f32 v[28:29], v[46:47], v[20:21], v[16:17]
	v_pk_fma_f32 v[30:31], v[48:49], v[18:19], v[14:15]
	v_pk_mul_f32 v[18:19], v[64:65], v[22:23] op_sel_hi:[0,1]
	v_pk_mul_f32 v[20:21], v[64:65], v[24:25] op_sel_hi:[0,1]
	v_pk_fma_f32 v[26:27], v[38:39], v[26:27], v[8:9]
	v_pk_fma_f32 v[58:59], v[40:41], v[58:59], v[6:7]
	v_pk_fma_f32 v[22:23], v[50:51], v[20:21], v[12:13]
	v_pk_fma_f32 v[24:25], v[52:53], v[18:19], v[10:11]
	v_lshl_add_u64 v[32:33], v[56:57], 0, s[34:35]
	v_cvt_pk_bf16_f32 v18, v58, v59
	v_cvt_pk_bf16_f32 v19, v26, v27
	v_cvt_pk_bf16_f32 v20, v62, v63
	v_cvt_pk_bf16_f32 v21, v60, v61
	global_store_dwordx4 v[32:33], v[18:21], off
	s_lshl_b64 s[4:5], s[36:37], 12
	s_add_u32 s4, s6, s4
	v_cvt_pk_bf16_f32 v18, v30, v31
	v_cvt_pk_bf16_f32 v19, v28, v29
	v_cvt_pk_bf16_f32 v20, v24, v25
	v_cvt_pk_bf16_f32 v21, v22, v23
	ds_read_b128 v[64:67], v72
	ds_read_b128 v[74:77], v72 offset:16
	global_store_dwordx4 v[32:33], v[18:21], off offset:1024
	ds_read_b128 v[18:21], v72 offset:12288
	s_addc_u32 s5, s7, s5
	s_waitcnt lgkmcnt(2)
	v_mul_f32_e32 v55, v59, v65
	v_fmac_f32_e32 v55, v58, v64
	v_mul_f32_e32 v64, v27, v67
	v_fmac_f32_e32 v64, v26, v66
	v_add_f32_e32 v55, v55, v64
	ds_read_b128 v[64:67], v72 offset:2048
	s_waitcnt lgkmcnt(2)
	v_mul_f32_e32 v73, v63, v75
	v_fmac_f32_e32 v73, v62, v74
	v_mul_f32_e32 v74, v61, v77
	v_fmac_f32_e32 v74, v60, v76
	v_add_f32_e32 v73, v73, v74
	ds_read_b128 v[74:77], v72 offset:2064
	s_waitcnt lgkmcnt(1)
	v_mul_f32_e32 v65, v31, v65
	v_fmac_f32_e32 v65, v30, v64
	v_mul_f32_e32 v64, v29, v67
	v_add_f32_e32 v55, 0, v55
	v_fmac_f32_e32 v64, v28, v66
	v_add_f32_e32 v55, v55, v73
	v_add_f32_e32 v64, v65, v64
	v_add_f32_e32 v55, v55, v64
	s_waitcnt lgkmcnt(0)
	v_mul_f32_e32 v64, v25, v75
	v_mul_f32_e32 v65, v23, v77
	v_fmac_f32_e32 v64, v24, v74
	v_fmac_f32_e32 v65, v22, v76
	v_add_f32_e32 v64, v64, v65
	v_add_f32_e32 v55, v55, v64
	ds_bpermute_b32 v64, v165, v55
	ds_read_b128 v[74:77], v72 offset:4112
	v_cmp_eq_u32_e64 s[6:7], 2, v1
	s_waitcnt lgkmcnt(1)
	v_add_f32_e32 v55, v55, v64
	ds_bpermute_b32 v64, v169, v55
	s_waitcnt lgkmcnt(1)
	v_mul_f32_e32 v75, v63, v75
	v_fmac_f32_e32 v75, v62, v74
	v_mul_f32_e32 v74, v61, v77
	v_fmac_f32_e32 v74, v60, v76
	s_waitcnt lgkmcnt(0)
	v_add_f32_e32 v55, v55, v64
	ds_read_b128 v[64:67], v72 offset:4096
	v_add_f32_e32 v74, v75, v74
	ds_bpermute_b32 v73, v168, v55
	s_waitcnt lgkmcnt(1)
	v_mul_f32_e32 v65, v59, v65
	v_fmac_f32_e32 v65, v58, v64
	v_mul_f32_e32 v64, v27, v67
	v_fmac_f32_e32 v64, v26, v66
	v_add_f32_e32 v64, v65, v64
	v_add_f32_e32 v78, 0, v64
	ds_read_b128 v[64:67], v72 offset:6144
	v_add_f32_e32 v78, v78, v74
	ds_read_b128 v[74:77], v72 offset:6160
	s_waitcnt lgkmcnt(2)
	v_add_f32_e32 v55, v55, v73
	ds_bpermute_b32 v73, v167, v55
	s_waitcnt lgkmcnt(2)
	v_mul_f32_e32 v65, v31, v65
	v_fmac_f32_e32 v65, v30, v64
	v_mul_f32_e32 v64, v29, v67
	v_fmac_f32_e32 v64, v28, v66
	v_add_f32_e32 v64, v65, v64
	s_waitcnt lgkmcnt(1)
	v_mul_f32_e32 v65, v25, v75
	v_mul_f32_e32 v66, v23, v77
	v_fmac_f32_e32 v65, v24, v74
	v_fmac_f32_e32 v66, v22, v76
	v_add_f32_e32 v64, v78, v64
	v_add_f32_e32 v65, v65, v66
	v_add_f32_e32 v64, v64, v65
	ds_bpermute_b32 v65, v165, v64
	s_waitcnt lgkmcnt(1)
	v_add_f32_e32 v55, v55, v73
	ds_bpermute_b32 v74, v166, v55
	v_lshlrev_b32_e32 v73, 3, v1
	s_waitcnt lgkmcnt(1)
	v_add_f32_e32 v75, v64, v65
	ds_bpermute_b32 v76, v169, v75
	ds_read_b128 v[64:67], v72 offset:8192
	s_waitcnt lgkmcnt(2)
	v_add_f32_e32 v55, v55, v74
	s_waitcnt lgkmcnt(1)
	v_add_f32_e32 v78, v75, v76
	ds_read_b128 v[74:77], v72 offset:8208
	s_waitcnt lgkmcnt(1)
	v_mul_f32_e32 v65, v59, v65
	v_fmac_f32_e32 v65, v58, v64
	v_mul_f32_e32 v64, v27, v67
	v_fmac_f32_e32 v64, v26, v66
	v_add_f32_e32 v64, v65, v64
	s_waitcnt lgkmcnt(0)
	v_mul_f32_e32 v75, v63, v75
	v_add_f32_e32 v80, 0, v64
	v_fmac_f32_e32 v75, v62, v74
	v_mul_f32_e32 v74, v61, v77
	ds_read_b128 v[64:67], v72 offset:10240
	v_fmac_f32_e32 v74, v60, v76
	v_add_f32_e32 v74, v75, v74
	v_add_f32_e32 v80, v80, v74
	ds_read_b128 v[74:77], v72 offset:10256
	s_waitcnt lgkmcnt(1)
; #define GAS __attribute__((address_space(1)))
; #define LAS __attribute__((address_space(3)))
; __device__ __forceinline__ unsigned pk2(float lo, float hi) { return pg8::cvt_pk_bf16(lo, hi); }
; template <int LO, int HI> __global__ void __launch_bounds__(NWAVES * 64, 2) fox_fwd(Args args) {
;     ...
;         for (int r = 0; r < 16; ++r) { const int m = m0 + r;
;             const GAS float* xr = (const GAS float*)(x + (size_t)m * D);
;             f32x4 v[4]; float s2 = 0.f;
; #pragma unroll
;             for (int j = 0; j < 4; ++j) { v[j] = *(const GAS f32x4*)(xr + P1COL(j)); s2 += (v[j][0] * v[j][0] + v[j][1] * v[j][1]) + (v[j][2] * v[j][2] + v[j][3] * v[j][3]); }
;             const float rstd = 1.0f / sqrtf(wave_sum(s2) * (1.0f / D) + EPS);
; #pragma unroll
;             for (int j = 0; j < 4; ++j) v[j] = v[j] * rstd * gm[j] + sh[j];
; #pragma unroll
;             for (int j = 0; j < 2; ++j) { v4u o; o.x = pk2(v[2 * j][0], v[2 * j][1]); o.y = pk2(v[2 * j][2], v[2 * j][3]); o.z = pk2(v[2 * j + 1][0], v[2 * j + 1][1]); o.w = pk2(v[2 * j + 1][2], v[2 * j + 1][3]);
;                 *(GAS v4u*)(HB + (size_t)m * D + 8 * lane + 512 * j) = o; }
;             float fl[8];
; #pragma unroll
;             for (int q = 0; q < 8; ++q) { float a = 0.f;
; #pragma unroll
;                 for (int j = 0; j < 4; ++j) { const f32x4 w = *(const LAS f32x4*)(wf + q * 1024 + P1COL(j)); a += (v[j][0] * w[0] + v[j][1] * w[1]) + (v[j][2] * w[2] + v[j][3] * w[3]); }
;                 fl[q] = wave_sum(a); }
	v_mul_f32_e32 v65, v31, v65
	ds_bpermute_b32 v79, v168, v78
	v_fmac_f32_e32 v65, v30, v64
	v_mul_f32_e32 v64, v29, v67
	v_fmac_f32_e32 v64, v28, v66
	v_add_f32_e32 v64, v65, v64
	s_waitcnt lgkmcnt(1)
	v_mul_f32_e32 v65, v25, v75
	v_mul_f32_e32 v66, v23, v77
	v_fmac_f32_e32 v65, v24, v74
	v_fmac_f32_e32 v66, v22, v76
	v_add_f32_e32 v64, v80, v64
	v_add_f32_e32 v65, v65, v66
	v_add_f32_e32 v64, v64, v65
	s_waitcnt lgkmcnt(0)
	v_add_f32_e32 v67, v78, v79
	ds_bpermute_b32 v65, v165, v64
	ds_bpermute_b32 v66, v164, v55
	ds_bpermute_b32 v74, v167, v67
	s_waitcnt lgkmcnt(2)
	v_add_f32_e32 v32, v64, v65
	s_waitcnt lgkmcnt(1)
	v_add_f32_e32 v55, v55, v66
	s_waitcnt lgkmcnt(0)
	v_add_f32_e32 v74, v67, v74
	ds_read_b128 v[64:67], v72 offset:12304
	v_mul_f32_e32 v19, v59, v19
	v_fmac_f32_e32 v19, v58, v18
	v_mul_f32_e32 v18, v27, v21
	v_fmac_f32_e32 v18, v26, v20
	v_add_f32_e32 v18, v19, v18
	s_waitcnt lgkmcnt(0)
	v_mul_f32_e32 v65, v63, v65
	v_add_f32_e32 v76, 0, v18
	v_fmac_f32_e32 v65, v62, v64
	v_mul_f32_e32 v64, v61, v67
	ds_read_b128 v[18:21], v72 offset:14336
	v_fmac_f32_e32 v64, v60, v66
	v_add_f32_e32 v64, v65, v64
	v_add_f32_e32 v76, v76, v64
	ds_read_b128 v[64:67], v72 offset:14352
	s_waitcnt lgkmcnt(1)
	v_mul_f32_e32 v19, v31, v19
	v_fmac_f32_e32 v19, v30, v18
	v_mul_f32_e32 v18, v29, v21
	v_fmac_f32_e32 v18, v28, v20
	v_add_f32_e32 v18, v19, v18
	s_waitcnt lgkmcnt(0)
	v_mul_f32_e32 v19, v25, v65
	v_mul_f32_e32 v20, v23, v67
	v_fmac_f32_e32 v19, v24, v64
	v_fmac_f32_e32 v20, v22, v66
	v_add_f32_e32 v18, v76, v18
	v_add_f32_e32 v19, v19, v20
	v_add_f32_e32 v64, v18, v19
	ds_bpermute_b32 v75, v166, v74
	ds_bpermute_b32 v65, v165, v64
	ds_read_b128 v[18:21], v72 offset:16384
	ds_bpermute_b32 v33, v169, v32
	s_waitcnt lgkmcnt(3)
	v_add_f32_e32 v74, v74, v75
	s_waitcnt lgkmcnt(2)
	v_add_f32_e32 v75, v64, v65
	ds_read_b128 v[64:67], v72 offset:16400
	s_waitcnt lgkmcnt(2)
	v_mul_f32_e32 v19, v59, v19
	v_fmac_f32_e32 v19, v58, v18
	v_mul_f32_e32 v18, v27, v21
	v_fmac_f32_e32 v18, v26, v20
	v_add_f32_e32 v18, v19, v18
	s_waitcnt lgkmcnt(0)
	v_mul_f32_e32 v65, v63, v65
	v_add_f32_e32 v77, 0, v18
	v_fmac_f32_e32 v65, v62, v64
	v_mul_f32_e32 v64, v61, v67
	ds_read_b128 v[18:21], v72 offset:18432
	v_fmac_f32_e32 v64, v60, v66
	v_add_f32_e32 v64, v65, v64
	v_add_f32_e32 v32, v32, v33
	v_add_f32_e32 v77, v77, v64
	ds_read_b128 v[64:67], v72 offset:18448
	ds_bpermute_b32 v33, v168, v32
	s_waitcnt lgkmcnt(2)
	v_mul_f32_e32 v19, v31, v19
	v_fmac_f32_e32 v19, v30, v18
	v_mul_f32_e32 v18, v29, v21
	v_fmac_f32_e32 v18, v28, v20
	v_add_f32_e32 v18, v19, v18
	s_waitcnt lgkmcnt(1)
	v_mul_f32_e32 v19, v25, v65
	v_mul_f32_e32 v20, v23, v67
	s_waitcnt lgkmcnt(0)
	v_add_f32_e32 v32, v32, v33
	ds_bpermute_b32 v76, v169, v75
	v_fmac_f32_e32 v19, v24, v64
	v_fmac_f32_e32 v20, v22, v66
	ds_bpermute_b32 v33, v167, v32
	v_add_f32_e32 v18, v77, v18
	v_add_f32_e32 v19, v19, v20
	v_add_f32_e32 v18, v18, v19
	ds_bpermute_b32 v19, v165, v18
	s_waitcnt lgkmcnt(2)
	v_add_f32_e32 v21, v75, v76
	s_waitcnt lgkmcnt(1)
	v_add_f32_e32 v20, v32, v33
	ds_bpermute_b32 v32, v168, v21
	ds_bpermute_b32 v33, v166, v20
	s_waitcnt lgkmcnt(2)
	v_add_f32_e32 v18, v18, v19
	ds_bpermute_b32 v19, v169, v18
	ds_bpermute_b32 v64, v164, v74
	s_waitcnt lgkmcnt(3)
	v_add_f32_e32 v21, v21, v32
	ds_bpermute_b32 v32, v167, v21
	s_waitcnt lgkmcnt(3)
	v_add_f32_e32 v20, v20, v33
	s_waitcnt lgkmcnt(2)
	v_add_f32_e32 v18, v18, v19
	ds_bpermute_b32 v19, v168, v18
	ds_bpermute_b32 v33, v164, v20
	s_waitcnt lgkmcnt(2)
	v_add_f32_e32 v21, v21, v32
	ds_bpermute_b32 v32, v166, v21
	v_add_f32_e32 v74, v74, v64
	s_waitcnt lgkmcnt(2)
	v_add_f32_e32 v64, v18, v19
	ds_bpermute_b32 v65, v167, v64
	s_waitcnt lgkmcnt(2)
	v_add_f32_e32 v75, v20, v33
	s_waitcnt lgkmcnt(1)
	v_add_f32_e32 v32, v21, v32
	ds_read_b128 v[18:21], v72 offset:20480
	ds_bpermute_b32 v33, v164, v32
	s_waitcnt lgkmcnt(2)
	v_add_f32_e32 v76, v64, v65
	ds_read_b128 v[64:67], v72 offset:20496
	ds_bpermute_b32 v77, v166, v76
	s_waitcnt lgkmcnt(3)
	v_mul_f32_e32 v19, v59, v19
	v_fmac_f32_e32 v19, v58, v18
	v_mul_f32_e32 v18, v27, v21
	v_fmac_f32_e32 v18, v26, v20
	v_add_f32_e32 v18, v19, v18
	s_waitcnt lgkmcnt(1)
	v_mul_f32_e32 v65, v63, v65
	v_add_f32_e32 v78, 0, v18
	v_fmac_f32_e32 v65, v62, v64
	v_mul_f32_e32 v64, v61, v67
	ds_read_b128 v[18:21], v72 offset:22528
	v_fmac_f32_e32 v64, v60, v66
	v_add_f32_e32 v64, v65, v64
	v_add_f32_e32 v78, v78, v64
	ds_read_b128 v[64:67], v72 offset:22544
	s_waitcnt lgkmcnt(1)
	v_mul_f32_e32 v19, v31, v19
	v_fmac_f32_e32 v19, v30, v18
	v_mul_f32_e32 v18, v29, v21
	v_fmac_f32_e32 v18, v28, v20
	v_add_f32_e32 v18, v19, v18
	s_waitcnt lgkmcnt(0)
	v_mul_f32_e32 v19, v25, v65
	v_mul_f32_e32 v20, v23, v67
	v_fmac_f32_e32 v19, v24, v64
	v_fmac_f32_e32 v20, v22, v66
	v_add_f32_e32 v18, v78, v18
	v_add_f32_e32 v19, v19, v20
	v_add_f32_e32 v64, v18, v19
	ds_bpermute_b32 v65, v165, v64
	ds_read_b128 v[18:21], v72 offset:24576
	v_add_f32_e32 v92, v32, v33
	v_add_f32_e32 v93, v76, v77
	ds_bpermute_b32 v94, v164, v93
	s_waitcnt lgkmcnt(2)
	v_add_f32_e32 v95, v64, v65
	ds_read_b128 v[64:67], v72 offset:24592
	s_waitcnt lgkmcnt(2)
	v_pk_mul_f32 v[18:19], v[58:59], v[18:19]
	v_pk_mul_f32 v[20:21], v[26:27], v[20:21]
	ds_bpermute_b32 v96, v169, v95
	v_pk_mov_b32 v[32:33], v[18:19], v[20:21] op_sel:[1,0]
	v_mov_b32_e32 v19, v21
	v_pk_add_f32 v[18:19], v[32:33], v[18:19]
	s_waitcnt lgkmcnt(1)
	v_pk_mul_f32 v[64:65], v[62:63], v[64:65]
	v_add_f32_e32 v18, v18, v19
	v_add_f32_e32 v32, 0, v18
	ds_read_b128 v[18:21], v72 offset:26624
	ds_read_b128 v[76:79], v72 offset:26640
	global_load_dwordx4 v[80:83], v54, s[4:5] offset:16
	global_load_dwordx4 v[84:87], v54, s[4:5]
	v_pk_mul_f32 v[66:67], v[60:61], v[66:67]
	s_waitcnt lgkmcnt(0)
; #define GAS __attribute__((address_space(1)))
; #define LAS __attribute__((address_space(3)))
; __device__ __forceinline__ unsigned pk2(float lo, float hi) { return pg8::cvt_pk_bf16(lo, hi); }
; template <int LO, int HI> __global__ void __launch_bounds__(NWAVES * 64, 2) fox_fwd(Args args) {
;     ...
;         for (int r = 0; r < 16; ++r) { const int m = m0 + r;
;             const GAS float* xr = (const GAS float*)(x + (size_t)m * D);
;             f32x4 v[4]; float s2 = 0.f;
; #pragma unroll
;             for (int j = 0; j < 4; ++j) { v[j] = *(const GAS f32x4*)(xr + P1COL(j)); s2 += (v[j][0] * v[j][0] + v[j][1] * v[j][1]) + (v[j][2] * v[j][2] + v[j][3] * v[j][3]); }
;             const float rstd = 1.0f / sqrtf(wave_sum(s2) * (1.0f / D) + EPS);
; #pragma unroll
;             for (int j = 0; j < 4; ++j) v[j] = v[j] * rstd * gm[j] + sh[j];
; #pragma unroll
;             for (int j = 0; j < 2; ++j) { v4u o; o.x = pk2(v[2 * j][0], v[2 * j][1]); o.y = pk2(v[2 * j][2], v[2 * j][3]); o.z = pk2(v[2 * j + 1][0], v[2 * j + 1][1]); o.w = pk2(v[2 * j + 1][2], v[2 * j + 1][3]);
;                 *(GAS v4u*)(HB + (size_t)m * D + 8 * lane + 512 * j) = o; }
;             float fl[8];
; #pragma unroll
;             for (int q = 0; q < 8; ++q) { float a = 0.f;
; #pragma unroll
;                 for (int j = 0; j < 4; ++j) { const f32x4 w = *(const LAS f32x4*)(wf + q * 1024 + P1COL(j)); a += (v[j][0] * w[0] + v[j][1] * w[1]) + (v[j][2] * w[2] + v[j][3] * w[3]); }
;                 fl[q] = wave_sum(a); }
;             float mine = fl[0];
; #pragma unroll
;             for (int q = 1; q < 8; ++q) mine = (lane == q) ? fl[q] : mine;
;             { const float z = mine + bfv; const float ls = fminf(z, 0.f) - log1pf(__expf(-fabsf(z)));
	v_mul_f32_e32 v33, v24, v76
	v_pk_mov_b32 v[88:89], v[64:65], v[66:67] op_sel:[1,0]
	v_mov_b32_e32 v65, v67
	v_pk_add_f32 v[64:65], v[88:89], v[64:65]
	v_mul_f32_e32 v66, v25, v77
	v_mul_f32_e32 v67, v22, v78
	v_mul_f32_e32 v97, v23, v79
	global_load_dwordx4 v[76:79], v54, s[4:5] offset:2048
	global_load_dwordx4 v[88:91], v54, s[4:5] offset:2064
	v_pk_add_f32 v[64:65], v[64:65], v[64:65] op_sel:[0,1] op_sel_hi:[1,0]
	v_cmp_eq_u32_e64 s[4:5], 1, v1
	v_mov_b32_e32 v65, v66
	v_pk_add_f32 v[32:33], v[32:33], v[64:65]
	v_mul_f32_e32 v64, v31, v19
	v_pk_fma_f32 v[18:19], v[30:31], v[18:19], v[64:65] op_sel_hi:[1,1,0]
	v_mul_f32_e32 v64, v29, v21
	v_pk_fma_f32 v[20:21], v[28:29], v[20:21], v[64:65] op_sel_hi:[1,1,0]
	v_mov_b32_e32 v19, v67
	v_mov_b32_e32 v21, v97
	v_pk_add_f32 v[64:65], v[18:19], v[20:21]
	ds_read_b128 v[18:21], v72 offset:28672
	v_pk_add_f32 v[32:33], v[32:33], v[64:65]
	ds_read_b128 v[64:67], v72 offset:28688
	v_add_f32_e32 v97, v32, v33
	ds_bpermute_b32 v98, v165, v97
	s_waitcnt lgkmcnt(2)
	v_pk_mul_f32 v[18:19], v[58:59], v[18:19]
	v_pk_mul_f32 v[20:21], v[26:27], v[20:21]
	s_waitcnt lgkmcnt(1)
	v_pk_mul_f32 v[32:33], v[62:63], v[64:65]
	v_pk_mov_b32 v[26:27], v[18:19], v[20:21] op_sel:[1,0]
	v_mov_b32_e32 v19, v21
	v_pk_add_f32 v[18:19], v[26:27], v[18:19]
	v_pk_mul_f32 v[58:59], v[60:61], v[66:67]
	v_add_f32_e32 v18, v18, v19
	v_add_f32_e32 v26, 0, v18
	ds_read_b128 v[18:21], v72 offset:30720
	ds_read_b128 v[62:65], v72 offset:30736
	v_pk_mov_b32 v[60:61], v[32:33], v[58:59] op_sel:[1,0]
	v_mov_b32_e32 v33, v59
	v_pk_add_f32 v[32:33], v[60:61], v[32:33]
	s_waitcnt lgkmcnt(0)
	v_mul_f32_e32 v27, v24, v62
	v_mul_f32_e32 v24, v25, v63
	v_mul_f32_e32 v25, v22, v64
	v_mul_f32_e32 v58, v23, v65
	v_pk_add_f32 v[22:23], v[32:33], v[32:33] op_sel:[0,1] op_sel_hi:[1,0]
	s_nop 0
	v_mov_b32_e32 v23, v24
	v_mul_f32_e32 v24, v31, v19
	v_pk_fma_f32 v[18:19], v[30:31], v[18:19], v[24:25] op_sel_hi:[1,1,0]
	v_mul_f32_e32 v24, v29, v21
	v_pk_fma_f32 v[20:21], v[28:29], v[20:21], v[24:25] op_sel_hi:[1,1,0]
	v_mov_b32_e32 v19, v25
	v_mov_b32_e32 v21, v58
	v_pk_add_f32 v[22:23], v[26:27], v[22:23]
	v_pk_add_f32 v[18:19], v[18:19], v[20:21]
	v_add_f32_e32 v20, v95, v96
	v_pk_add_f32 v[18:19], v[22:23], v[18:19]
	ds_bpermute_b32 v21, v168, v20
	v_add_f32_e32 v18, v18, v19
	ds_bpermute_b32 v19, v165, v18
	v_add_f32_e32 v22, v97, v98
	ds_bpermute_b32 v23, v169, v22
	s_waitcnt lgkmcnt(2)
	v_add_f32_e32 v20, v20, v21
	ds_bpermute_b32 v21, v167, v20
	s_waitcnt lgkmcnt(2)
	v_add_f32_e32 v18, v18, v19
	ds_bpermute_b32 v19, v169, v18
	s_waitcnt lgkmcnt(2)
	v_add_f32_e32 v22, v22, v23
	ds_bpermute_b32 v23, v168, v22
	s_waitcnt lgkmcnt(2)
	v_add_f32_e32 v20, v20, v21
	ds_bpermute_b32 v21, v166, v20
	s_waitcnt lgkmcnt(2)
	v_add_f32_e32 v18, v18, v19
	ds_bpermute_b32 v19, v168, v18
	s_waitcnt lgkmcnt(2)
	v_add_f32_e32 v22, v22, v23
	ds_bpermute_b32 v23, v167, v22
	s_waitcnt lgkmcnt(2)
	v_add_f32_e32 v26, v20, v21
	ds_bpermute_b32 v27, v164, v26
	s_waitcnt lgkmcnt(2)
	v_add_f32_e32 v18, v18, v19
	ds_bpermute_b32 v19, v167, v18
	s_waitcnt vmcnt(2)
	v_pk_mul_f32 v[20:21], v[84:85], v[84:85]
	s_waitcnt lgkmcnt(2)
	v_add_f32_e32 v28, v22, v23
	ds_bpermute_b32 v29, v166, v28
	s_waitcnt lgkmcnt(1)
	v_add_f32_e32 v30, v18, v19
	v_pk_mul_f32 v[18:19], v[86:87], v[86:87]
	ds_bpermute_b32 v31, v166, v30
	v_pk_mov_b32 v[22:23], v[20:21], v[18:19] op_sel:[1,0]
	v_mov_b32_e32 v21, v19
	v_pk_add_f32 v[18:19], v[22:23], v[20:21]
	v_pk_mul_f32 v[20:21], v[82:83], v[82:83]
	v_pk_mul_f32 v[22:23], v[80:81], v[80:81]
	v_pk_add_f32 v[18:19], v[18:19], v[18:19] op_sel:[0,1] op_sel_hi:[1,0]
	v_pk_mov_b32 v[24:25], v[22:23], v[20:21] op_sel:[1,0]
	v_mov_b32_e32 v23, v21
	v_pk_add_f32 v[20:21], v[24:25], v[22:23]
	s_waitcnt vmcnt(0)
	v_mul_f32_e32 v22, v88, v88
	v_mul_f32_e32 v23, v89, v89
	v_pk_add_f32 v[20:21], v[20:21], v[20:21] op_sel:[0,1] op_sel_hi:[1,0]
	v_mov_b32_e32 v19, v22
	v_mov_b32_e32 v21, v23
	v_pk_add_f32 v[18:19], v[18:19], v[20:21]
	v_mul_f32_e32 v20, v77, v77
	v_mul_f32_e32 v22, v79, v79
	v_mul_f32_e32 v24, v90, v90
	v_mul_f32_e32 v25, v91, v91
	v_pk_fma_f32 v[20:21], v[76:77], v[76:77], v[20:21] op_sel_hi:[1,1,0]
	v_pk_fma_f32 v[22:23], v[78:79], v[78:79], v[22:23] op_sel_hi:[1,1,0]
	v_mov_b32_e32 v21, v24
	v_mov_b32_e32 v23, v25
	v_pk_add_f32 v[20:21], v[20:21], v[22:23]
	s_waitcnt lgkmcnt(0)
	v_add_f32_e32 v22, v30, v31
	v_pk_add_f32 v[18:19], v[18:19], v[20:21]
	v_add_f32_e32 v20, v28, v29
	v_add_f32_e32 v18, v18, v19
	ds_bpermute_b32 v19, v165, v18
	ds_bpermute_b32 v21, v164, v20
	ds_bpermute_b32 v23, v164, v22
	v_add_f32_e32 v24, v93, v94
	v_add_f32_e32 v25, v26, v27
	s_waitcnt lgkmcnt(2)
	v_add_f32_e32 v18, v18, v19
	ds_bpermute_b32 v19, v169, v18
	s_waitcnt lgkmcnt(2)
	v_add_f32_e32 v20, v20, v21
	s_waitcnt lgkmcnt(1)
	v_add_f32_e32 v21, v22, v23
	v_cndmask_b32_e64 v22, v55, v74, s[4:5]
	v_cndmask_b32_e64 v22, v22, v75, s[6:7]
	s_waitcnt lgkmcnt(0)
	v_add_f32_e32 v18, v18, v19
	ds_bpermute_b32 v19, v168, v18
	v_cndmask_b32_e64 v22, v22, v92, s[8:9]
	v_cndmask_b32_e64 v22, v22, v24, s[10:11]
	v_cndmask_b32_e64 v22, v22, v25, s[12:13]
	v_cndmask_b32_e64 v20, v22, v20, s[14:15]
	s_waitcnt lgkmcnt(0)
	v_add_f32_e32 v18, v18, v19
	ds_bpermute_b32 v19, v167, v18
	v_cndmask_b32_e64 v20, v20, v21, s[16:17]
	v_add_f32_e32 v20, v71, v20
	v_min_f32_e32 v22, 0, v20
	v_mul_f32_e64 v20, |v20|, s29
	s_waitcnt lgkmcnt(0)
	v_add_f32_e32 v18, v18, v19
	ds_bpermute_b32 v19, v166, v18
	v_exp_f32_e32 v55, v20
	s_waitcnt lgkmcnt(0)
	v_add_f32_e32 v18, v18, v19
	ds_bpermute_b32 v19, v164, v18
	v_add_f32_e32 v92, 1.0, v55
	v_add_f32_e32 v23, -1.0, v92
	v_sub_f32_e32 v26, v23, v92
	v_add_f32_e32 v26, 1.0, v26
	s_waitcnt lgkmcnt(0)
; #define GAS __attribute__((address_space(1)))
; #define LAS __attribute__((address_space(3)))
; __device__ __forceinline__ unsigned pk2(float lo, float hi) { return pg8::cvt_pk_bf16(lo, hi); }
; template <int LO, int HI> __global__ void __launch_bounds__(NWAVES * 64, 2) fox_fwd(Args args) {
;     ...
;             for (int j = 0; j < 4; ++j) { v[j] = *(const GAS f32x4*)(xr + P1COL(j)); s2 += (v[j][0] * v[j][0] + v[j][1] * v[j][1]) + (v[j][2] * v[j][2] + v[j][3] * v[j][3]); }
;             const float rstd = 1.0f / sqrtf(wave_sum(s2) * (1.0f / D) + EPS);
; #pragma unroll
;             for (int j = 0; j < 4; ++j) v[j] = v[j] * rstd * gm[j] + sh[j];
; #pragma unroll
;             for (int j = 0; j < 2; ++j) { v4u o; o.x = pk2(v[2 * j][0], v[2 * j][1]); o.y = pk2(v[2 * j][2], v[2 * j][3]); o.z = pk2(v[2 * j + 1][0], v[2 * j + 1][1]); o.w = pk2(v[2 * j + 1][2], v[2 * j + 1][3]);
;                 *(GAS v4u*)(HB + (size_t)m * D + 8 * lane + 512 * j) = o; }
;             float fl[8];
; #pragma unroll
;             for (int q = 0; q < 8; ++q) { float a = 0.f;
; #pragma unroll
;                 for (int j = 0; j < 4; ++j) { const f32x4 w = *(const LAS f32x4*)(wf + q * 1024 + P1COL(j)); a += (v[j][0] * w[0] + v[j][1] * w[1]) + (v[j][2] * w[2] + v[j][3] * w[3]); }
;                 fl[q] = wave_sum(a); }
;             float mine = fl[0];
; #pragma unroll
;             for (int q = 1; q < 8; ++q) mine = (lane == q) ? fl[q] : mine;
;             { const float z = mine + bfv; const float ls = fminf(z, 0.f) - log1pf(__expf(-fabsf(z)));
	v_add_f32_e32 v18, v18, v19
	v_fmamk_f32 v18, v18, 0x3a800000, v69
	v_mul_f32_e32 v19, 0x4f800000, v18
	v_cmp_gt_f32_e32 vcc, s45, v18
	v_sub_f32_e32 v23, v55, v23
	v_add_f32_e32 v23, v23, v26
	v_cndmask_b32_e32 v18, v18, v19, vcc
	v_sqrt_f32_e32 v19, v18
	s_nop 0
	v_add_u32_e32 v20, -1, v19
	v_fma_f32 v21, -v20, v19, v18
	v_cmp_ge_f32_e64 s[20:21], 0, v21
	v_add_u32_e32 v21, 1, v19
	s_nop 0
	v_cndmask_b32_e64 v20, v19, v20, s[20:21]
	v_fma_f32 v19, -v21, v19, v18
	v_cmp_lt_f32_e64 s[20:21], 0, v19
	s_nop 1
	v_cndmask_b32_e64 v19, v20, v21, s[20:21]
	v_mul_f32_e32 v20, 0x37800000, v19
	v_cndmask_b32_e32 v19, v19, v20, vcc
	v_cmp_class_f32_e32 vcc, v18, v70
	s_nop 1
	v_cndmask_b32_e32 v18, v19, v18, vcc
	v_div_scale_f32 v19, s[20:21], v18, v18, 1.0
	v_rcp_f32_e32 v20, v19
	s_lshl_b64 s[20:21], s[36:37], 11
	s_mov_b32 s37, 0x3f2aaaab
	s_mov_b32 s36, 0x3f317218
	v_fma_f32 v21, -v19, v20, 1.0
	v_fmac_f32_e32 v20, v21, v20
	v_div_scale_f32 v21, vcc, 1.0, v18, 1.0
	v_mul_f32_e32 v24, v21, v20
	v_fma_f32 v25, -v19, v24, v21
	v_fmac_f32_e32 v24, v25, v20
	v_fma_f32 v19, -v19, v24, v21
	v_div_fmas_f32 v19, v19, v20, v24
	v_div_fixup_f32 v18, v19, v18, 1.0
	v_pk_mul_f32 v[20:21], v[18:19], v[84:85] op_sel_hi:[0,1]
	v_pk_mul_f32 v[24:25], v[18:19], v[86:87] op_sel_hi:[0,1]
	v_pk_fma_f32 v[64:65], v[40:41], v[20:21], v[6:7]
	v_pk_mul_f32 v[20:21], v[18:19], v[80:81] op_sel_hi:[0,1]
	v_pk_fma_f32 v[62:63], v[38:39], v[24:25], v[8:9]
	v_pk_mul_f32 v[24:25], v[18:19], v[82:83] op_sel_hi:[0,1]
	v_pk_fma_f32 v[66:67], v[44:45], v[20:21], v[2:3]
	v_pk_mul_f32 v[20:21], v[18:19], v[76:77] op_sel_hi:[0,1]
	v_pk_fma_f32 v[32:33], v[42:43], v[24:25], v[4:5]
	v_pk_mul_f32 v[24:25], v[18:19], v[78:79] op_sel_hi:[0,1]
	v_pk_fma_f32 v[30:31], v[48:49], v[20:21], v[14:15]
	v_pk_mul_f32 v[20:21], v[18:19], v[88:89] op_sel_hi:[0,1]
	v_pk_mul_f32 v[18:19], v[18:19], v[90:91] op_sel_hi:[0,1]
	v_pk_fma_f32 v[28:29], v[46:47], v[24:25], v[16:17]
	v_pk_fma_f32 v[58:59], v[50:51], v[18:19], v[12:13]
	v_pk_fma_f32 v[60:61], v[52:53], v[20:21], v[10:11]
	v_lshl_add_u64 v[24:25], v[56:57], 0, s[20:21]
	v_cvt_pk_bf16_f32 v18, v64, v65
	v_cvt_pk_bf16_f32 v19, v62, v63
	v_cvt_pk_bf16_f32 v20, v66, v67
	v_cvt_pk_bf16_f32 v21, v32, v33
	global_store_dwordx4 v[24:25], v[18:21], off
	s_mov_b32 s20, 0x3e9b6dac
	s_nop 0
	v_cvt_pk_bf16_f32 v18, v30, v31
	v_cvt_pk_bf16_f32 v19, v28, v29
	v_cvt_pk_bf16_f32 v20, v60, v61
	v_cvt_pk_bf16_f32 v21, v58, v59
	ds_read_b128 v[74:77], v72
	ds_read_b128 v[78:81], v72 offset:16
	s_waitcnt lgkmcnt(1)
	v_mul_f32_e32 v26, v65, v75
	v_mul_f32_e32 v27, v63, v77
	v_fmac_f32_e32 v26, v64, v74
	v_fmac_f32_e32 v27, v62, v76
	ds_read_b128 v[74:77], v72 offset:2048
	v_add_f32_e32 v26, v26, v27
	s_waitcnt lgkmcnt(1)
	v_mul_f32_e32 v27, v67, v79
	v_mul_f32_e32 v56, v33, v81
	v_fmac_f32_e32 v27, v66, v78
	v_fmac_f32_e32 v56, v32, v80
	ds_read_b128 v[78:81], v72 offset:2064
	v_add_f32_e32 v26, 0, v26
	v_add_f32_e32 v27, v27, v56
	v_add_f32_e32 v26, v26, v27
	s_waitcnt lgkmcnt(1)
	v_mul_f32_e32 v27, v31, v75
	v_mul_f32_e32 v56, v29, v77
	v_fmac_f32_e32 v27, v30, v74
	v_fmac_f32_e32 v56, v28, v76
	v_add_f32_e32 v27, v27, v56
	v_add_f32_e32 v26, v26, v27
	s_waitcnt lgkmcnt(0)
	v_mul_f32_e32 v27, v61, v79
	v_mul_f32_e32 v56, v59, v81
	v_fmac_f32_e32 v27, v60, v78
	v_fmac_f32_e32 v56, v58, v80
	v_add_f32_e32 v27, v27, v56
	v_add_f32_e32 v56, v26, v27
	ds_bpermute_b32 v57, v165, v56
	v_frexp_mant_f32_e32 v74, v92
	v_cmp_gt_f32_e32 vcc, s37, v74
	ds_read_b128 v[74:77], v72 offset:4096
	v_cvt_f64_f32_e32 v[26:27], v92
	s_waitcnt lgkmcnt(1)
	v_add_f32_e32 v57, v56, v57
	ds_bpermute_b32 v78, v169, v57
	v_frexp_exp_i32_f64_e32 v26, v[26:27]
	v_subbrev_co_u32_e32 v56, vcc, 0, v26, vcc
	v_sub_u32_e32 v27, 0, v56
	s_waitcnt lgkmcnt(0)
	v_add_f32_e32 v57, v57, v78
	ds_read_b128 v[78:81], v72 offset:4112
	v_mul_f32_e32 v26, v65, v75
	v_fmac_f32_e32 v26, v64, v74
	v_mul_f32_e32 v74, v63, v77
	v_fmac_f32_e32 v74, v62, v76
	v_add_f32_e32 v26, v26, v74
	s_waitcnt lgkmcnt(0)
	v_mul_f32_e32 v79, v67, v79
	ds_read_b128 v[74:77], v72 offset:6144
	v_fmac_f32_e32 v79, v66, v78
	v_mul_f32_e32 v78, v33, v81
	v_fmac_f32_e32 v78, v32, v80
	v_add_f32_e32 v26, 0, v26
	v_add_f32_e32 v78, v79, v78
	v_add_f32_e32 v26, v26, v78
	ds_read_b128 v[78:81], v72 offset:6160
	s_waitcnt lgkmcnt(1)
	v_mul_f32_e32 v75, v31, v75
	v_fmac_f32_e32 v75, v30, v74
	v_mul_f32_e32 v74, v29, v77
	v_fmac_f32_e32 v74, v28, v76
	v_add_f32_e32 v74, v75, v74
	v_add_f32_e32 v26, v26, v74
	s_waitcnt lgkmcnt(0)
	v_mul_f32_e32 v74, v61, v79
	v_mul_f32_e32 v75, v59, v81
	v_fmac_f32_e32 v74, v60, v78
	v_fmac_f32_e32 v75, v58, v80
	v_add_f32_e32 v74, v74, v75
	v_add_f32_e32 v78, v26, v74
	ds_bpermute_b32 v79, v165, v78
	ds_read_b128 v[74:77], v72 offset:8192
	ds_bpermute_b32 v82, v168, v57
	v_ldexp_f32 v26, v92, v27
	s_waitcnt lgkmcnt(2)
	v_add_f32_e32 v83, v78, v79
	ds_read_b128 v[78:81], v72 offset:8208
	s_waitcnt lgkmcnt(2)
	v_mul_f32_e32 v75, v65, v75
	v_fmac_f32_e32 v75, v64, v74
	v_mul_f32_e32 v74, v63, v77
	v_fmac_f32_e32 v74, v62, v76
	v_add_f32_e32 v74, v75, v74
	s_waitcnt lgkmcnt(0)
	v_mul_f32_e32 v79, v67, v79
	v_add_f32_e32 v85, 0, v74
	v_fmac_f32_e32 v79, v66, v78
	v_mul_f32_e32 v78, v33, v81
	ds_read_b128 v[74:77], v72 offset:10240
	v_fmac_f32_e32 v78, v32, v80
	v_add_f32_e32 v78, v79, v78
	v_add_f32_e32 v85, v85, v78
	ds_read_b128 v[78:81], v72 offset:10256
	s_waitcnt lgkmcnt(1)
	v_mul_f32_e32 v75, v31, v75
	v_fmac_f32_e32 v75, v30, v74
	v_mul_f32_e32 v74, v29, v77
	v_fmac_f32_e32 v74, v28, v76
	v_add_f32_e32 v57, v57, v82
	v_add_f32_e32 v74, v75, v74
	s_waitcnt lgkmcnt(0)
; #define LAS __attribute__((address_space(3)))
; template <int LO, int HI> __global__ void __launch_bounds__(NWAVES * 64, 2) fox_fwd(Args args) {
;     ...
;             for (int q = 0; q < 8; ++q) { float a = 0.f;
; #pragma unroll
;                 for (int j = 0; j < 4; ++j) { const f32x4 w = *(const LAS f32x4*)(wf + q * 1024 + P1COL(j)); a += (v[j][0] * w[0] + v[j][1] * w[1]) + (v[j][2] * w[2] + v[j][3] * w[3]); }
;                 fl[q] = wave_sum(a); }
	v_mul_f32_e32 v75, v61, v79
	v_mul_f32_e32 v76, v59, v81
	ds_bpermute_b32 v82, v167, v57
	v_fmac_f32_e32 v75, v60, v78
	v_fmac_f32_e32 v76, v58, v80
	v_add_f32_e32 v74, v85, v74
	v_add_f32_e32 v75, v75, v76
	v_add_f32_e32 v74, v74, v75
	ds_bpermute_b32 v84, v169, v83
	ds_bpermute_b32 v75, v165, v74
	s_waitcnt lgkmcnt(2)
	v_add_f32_e32 v57, v57, v82
	ds_bpermute_b32 v76, v166, v57
	s_waitcnt lgkmcnt(2)
	v_add_f32_e32 v77, v83, v84
	s_waitcnt lgkmcnt(1)
	v_add_f32_e32 v74, v74, v75
	ds_bpermute_b32 v78, v168, v77
	ds_bpermute_b32 v75, v169, v74
	s_waitcnt lgkmcnt(2)
	v_add_f32_e32 v57, v57, v76
	ds_bpermute_b32 v76, v164, v57
	s_waitcnt lgkmcnt(2)
	v_add_f32_e32 v78, v77, v78
	s_waitcnt lgkmcnt(1)
	v_add_f32_e32 v80, v74, v75
	ds_bpermute_b32 v79, v167, v78
	ds_bpermute_b32 v81, v168, v80
	s_waitcnt lgkmcnt(2)
	v_add_f32_e32 v57, v57, v76
	ds_read_b128 v[74:77], v72 offset:12288
	s_waitcnt lgkmcnt(2)
	v_add_f32_e32 v82, v78, v79
	s_waitcnt lgkmcnt(1)
	v_add_f32_e32 v84, v80, v81
	ds_read_b128 v[78:81], v72 offset:12304
	s_waitcnt lgkmcnt(1)
	v_mul_f32_e32 v75, v65, v75
	v_fmac_f32_e32 v75, v64, v74
	v_mul_f32_e32 v74, v63, v77
	v_fmac_f32_e32 v74, v62, v76
	v_add_f32_e32 v74, v75, v74
	s_waitcnt lgkmcnt(0)
	v_mul_f32_e32 v79, v67, v79
	v_add_f32_e32 v85, 0, v74
	v_fmac_f32_e32 v79, v66, v78
	v_mul_f32_e32 v78, v33, v81
	ds_read_b128 v[74:77], v72 offset:14336
	v_fmac_f32_e32 v78, v32, v80
	v_add_f32_e32 v78, v79, v78
	v_add_f32_e32 v85, v85, v78
	ds_read_b128 v[78:81], v72 offset:14352
	s_waitcnt lgkmcnt(1)
	v_mul_f32_e32 v75, v31, v75
	v_fmac_f32_e32 v75, v30, v74
	v_mul_f32_e32 v74, v29, v77
	v_fmac_f32_e32 v74, v28, v76
	v_add_f32_e32 v74, v75, v74
	s_waitcnt lgkmcnt(0)
	v_mul_f32_e32 v79, v61, v79
	v_add_f32_e32 v85, v85, v74
	v_fmac_f32_e32 v79, v60, v78
	v_mul_f32_e32 v78, v59, v81
	ds_read_b128 v[74:77], v72 offset:16384
	v_fmac_f32_e32 v78, v58, v80
	v_add_f32_e32 v78, v79, v78
	v_add_f32_e32 v85, v85, v78
	ds_read_b128 v[78:81], v72 offset:16400
	s_waitcnt lgkmcnt(1)
	v_mul_f32_e32 v75, v65, v75
	v_fmac_f32_e32 v75, v64, v74
	v_mul_f32_e32 v74, v63, v77
	v_fmac_f32_e32 v74, v62, v76
	v_add_f32_e32 v74, v75, v74
	s_waitcnt lgkmcnt(0)
	v_mul_f32_e32 v79, v67, v79
	v_add_f32_e32 v87, 0, v74
	v_fmac_f32_e32 v79, v66, v78
	v_mul_f32_e32 v78, v33, v81
	ds_read_b128 v[74:77], v72 offset:18432
	v_fmac_f32_e32 v78, v32, v80
	v_add_f32_e32 v78, v79, v78
	v_add_f32_e32 v87, v87, v78
	ds_read_b128 v[78:81], v72 offset:18448
	s_waitcnt lgkmcnt(1)
	v_mul_f32_e32 v75, v31, v75
	v_fmac_f32_e32 v75, v30, v74
	v_mul_f32_e32 v74, v29, v77
	v_fmac_f32_e32 v74, v28, v76
	v_add_f32_e32 v74, v75, v74
	s_waitcnt lgkmcnt(0)
	v_mul_f32_e32 v75, v61, v79
	v_mul_f32_e32 v76, v59, v81
	v_fmac_f32_e32 v75, v60, v78
	v_fmac_f32_e32 v76, v58, v80
	v_add_f32_e32 v74, v87, v74
	v_add_f32_e32 v75, v75, v76
	v_add_f32_e32 v74, v74, v75
	ds_bpermute_b32 v86, v165, v85
	ds_bpermute_b32 v75, v165, v74
	ds_bpermute_b32 v76, v167, v84
	ds_bpermute_b32 v83, v166, v82
	s_waitcnt lgkmcnt(3)
	v_add_f32_e32 v77, v85, v86
	s_waitcnt lgkmcnt(2)
	v_add_f32_e32 v74, v74, v75
	ds_bpermute_b32 v78, v169, v77
	ds_bpermute_b32 v75, v169, v74
	s_waitcnt lgkmcnt(3)
	v_add_f32_e32 v76, v84, v76
	ds_bpermute_b32 v80, v166, v76
	s_waitcnt lgkmcnt(3)
	v_add_f32_e32 v79, v82, v83
	s_waitcnt lgkmcnt(2)
	v_add_f32_e32 v77, v77, v78
	s_waitcnt lgkmcnt(1)
	v_add_f32_e32 v74, v74, v75
	ds_bpermute_b32 v78, v168, v77
	ds_bpermute_b32 v75, v168, v74
	ds_bpermute_b32 v81, v164, v79
	s_waitcnt lgkmcnt(3)
	v_add_f32_e32 v76, v76, v80
	ds_bpermute_b32 v82, v164, v76
	s_waitcnt lgkmcnt(3)
	v_add_f32_e32 v77, v77, v78
	s_waitcnt lgkmcnt(2)
	v_add_f32_e32 v75, v74, v75
	ds_bpermute_b32 v78, v167, v77
	ds_bpermute_b32 v80, v167, v75
	s_waitcnt lgkmcnt(3)
	v_add_f32_e32 v74, v79, v81
	s_waitcnt lgkmcnt(1)
	v_add_f32_e32 v77, v77, v78
	s_waitcnt lgkmcnt(0)
	v_add_f32_e32 v79, v75, v80
	ds_bpermute_b32 v78, v166, v77
	ds_bpermute_b32 v84, v166, v79
	v_add_f32_e32 v75, v76, v82
	ds_read_b128 v[80:83], v72 offset:20480
	s_waitcnt lgkmcnt(2)
	v_add_f32_e32 v76, v77, v78
	s_waitcnt lgkmcnt(1)
	v_add_f32_e32 v78, v79, v84
	ds_read_b128 v[84:87], v72 offset:20496
	s_waitcnt lgkmcnt(1)
	v_mul_f32_e32 v81, v65, v81
	v_fmac_f32_e32 v81, v64, v80
	v_mul_f32_e32 v80, v63, v83
	v_fmac_f32_e32 v80, v62, v82
	v_add_f32_e32 v80, v81, v80
	s_waitcnt lgkmcnt(0)
	v_mul_f32_e32 v85, v67, v85
	v_add_f32_e32 v88, 0, v80
	v_fmac_f32_e32 v85, v66, v84
	v_mul_f32_e32 v84, v33, v87
	ds_read_b128 v[80:83], v72 offset:22528
	v_fmac_f32_e32 v84, v32, v86
	v_add_f32_e32 v84, v85, v84
	v_add_f32_e32 v88, v88, v84
	ds_read_b128 v[84:87], v72 offset:22544
	s_waitcnt lgkmcnt(1)
	v_mul_f32_e32 v81, v31, v81
	v_fmac_f32_e32 v81, v30, v80
	v_mul_f32_e32 v80, v29, v83
	v_fmac_f32_e32 v80, v28, v82
	v_add_f32_e32 v80, v81, v80
	s_waitcnt lgkmcnt(0)
	v_mul_f32_e32 v81, v61, v85
	v_fmac_f32_e32 v81, v60, v84
	ds_read_b128 v[82:85], v72 offset:24576
	v_mul_f32_e32 v87, v59, v87
	v_fmac_f32_e32 v87, v58, v86
	v_add_f32_e32 v80, v88, v80
	v_add_f32_e32 v81, v81, v87
	ds_read_b128 v[86:89], v72 offset:24592
	s_waitcnt lgkmcnt(1)
	v_pk_mul_f32 v[82:83], v[64:65], v[82:83]
	v_pk_mul_f32 v[84:85], v[62:63], v[84:85]
	v_add_f32_e32 v80, v80, v81
	v_pk_mov_b32 v[90:91], v[82:83], v[84:85] op_sel:[1,0]
	v_mov_b32_e32 v83, v85
	v_pk_add_f32 v[82:83], v[90:91], v[82:83]
	s_waitcnt lgkmcnt(0)
	v_pk_mul_f32 v[86:87], v[66:67], v[86:87]
	v_add_f32_e32 v82, v82, v83
	v_add_f32_e32 v94, 0, v82
	ds_read_b128 v[82:85], v72 offset:26624
	ds_read_b128 v[90:93], v72 offset:26640
	v_pk_mul_f32 v[88:89], v[32:33], v[88:89]
	ds_bpermute_b32 v81, v165, v80
	v_pk_mov_b32 v[96:97], v[86:87], v[88:89] op_sel:[1,0]
	v_mov_b32_e32 v87, v89
	v_pk_add_f32 v[86:87], v[96:97], v[86:87]
	s_waitcnt lgkmcnt(1)
; #define LAS __attribute__((address_space(3)))
; template <int LO, int HI> __global__ void __launch_bounds__(NWAVES * 64, 2) fox_fwd(Args args) {
;     ...
;             for (int q = 0; q < 8; ++q) { float a = 0.f;
; #pragma unroll
;                 for (int j = 0; j < 4; ++j) { const f32x4 w = *(const LAS f32x4*)(wf + q * 1024 + P1COL(j)); a += (v[j][0] * w[0] + v[j][1] * w[1]) + (v[j][2] * w[2] + v[j][3] * w[3]); }
;                 fl[q] = wave_sum(a); }
;             float mine = fl[0];
; #pragma unroll
;             for (int q = 1; q < 8; ++q) mine = (lane == q) ? fl[q] : mine;
;             { const float z = mine + bfv; const float ls = fminf(z, 0.f) - log1pf(__expf(-fabsf(z)));
; #pragma unroll
;               for (int k = 0; k < 4; ++k)
; #pragma unroll
;                   for (int e = 0; e < 4; ++e) lsq[k][e] = (r == 4 * k + e) ? ls : lsq[k][e]; }
	v_mul_f32_e32 v88, v61, v91
	v_pk_add_f32 v[86:87], v[86:87], v[86:87] op_sel:[0,1] op_sel_hi:[1,0]
	v_mul_f32_e32 v95, v60, v90
	v_mov_b32_e32 v87, v88
	v_pk_add_f32 v[88:89], v[94:95], v[86:87]
	v_mul_f32_e32 v86, v31, v83
	v_pk_fma_f32 v[82:83], v[30:31], v[82:83], v[86:87] op_sel_hi:[1,1,0]
	v_mul_f32_e32 v86, v29, v85
	v_mul_f32_e32 v90, v58, v92
	v_mul_f32_e32 v91, v59, v93
	v_pk_fma_f32 v[84:85], v[28:29], v[84:85], v[86:87] op_sel_hi:[1,1,0]
	v_mov_b32_e32 v83, v90
	v_mov_b32_e32 v85, v91
	v_pk_add_f32 v[82:83], v[82:83], v[84:85]
	ds_read_b128 v[84:87], v72 offset:28672
	v_pk_add_f32 v[82:83], v[88:89], v[82:83]
	ds_read_b128 v[88:91], v72 offset:28688
	v_add_f32_e32 v82, v82, v83
	ds_bpermute_b32 v83, v165, v82
	s_waitcnt lgkmcnt(2)
	v_pk_mul_f32 v[64:65], v[64:65], v[84:85]
	v_pk_mul_f32 v[62:63], v[62:63], v[86:87]
	s_waitcnt lgkmcnt(1)
	v_pk_mul_f32 v[66:67], v[66:67], v[88:89]
	v_pk_mov_b32 v[84:85], v[64:65], v[62:63] op_sel:[1,0]
	v_mov_b32_e32 v65, v63
	v_pk_add_f32 v[62:63], v[84:85], v[64:65]
	v_pk_mul_f32 v[32:33], v[32:33], v[90:91]
	v_add_f32_e32 v62, v62, v63
	v_add_f32_e32 v92, 0, v62
	ds_read_b128 v[62:65], v72 offset:30720
	ds_read_b128 v[84:87], v72 offset:30736
	v_pk_mov_b32 v[88:89], v[66:67], v[32:33] op_sel:[1,0]
	v_mov_b32_e32 v67, v33
	v_pk_add_f32 v[32:33], v[88:89], v[66:67]
	ds_bpermute_b32 v77, v164, v76
	s_waitcnt lgkmcnt(1)
	v_mul_f32_e32 v93, v60, v84
	v_mul_f32_e32 v60, v61, v85
	v_mul_f32_e32 v61, v58, v86
	v_mul_f32_e32 v59, v59, v87
	v_mul_f32_e32 v58, v31, v63
	v_pk_fma_f32 v[30:31], v[30:31], v[62:63], v[58:59] op_sel_hi:[1,1,0]
	v_mul_f32_e32 v58, v29, v65
	v_pk_add_f32 v[32:33], v[32:33], v[32:33] op_sel:[0,1] op_sel_hi:[1,0]
	v_pk_fma_f32 v[28:29], v[28:29], v[64:65], v[58:59] op_sel_hi:[1,1,0]
	v_mov_b32_e32 v33, v60
	v_mov_b32_e32 v31, v61
	v_mov_b32_e32 v29, v59
	v_pk_add_f32 v[32:33], v[92:93], v[32:33]
	v_pk_add_f32 v[28:29], v[30:31], v[28:29]
	v_add_f32_e32 v30, v80, v81
	v_pk_add_f32 v[28:29], v[32:33], v[28:29]
	ds_bpermute_b32 v31, v169, v30
	v_add_f32_e32 v28, v28, v29
	ds_bpermute_b32 v29, v165, v28
	v_add_f32_e32 v32, v82, v83
	ds_bpermute_b32 v33, v169, v32
	s_waitcnt lgkmcnt(2)
	v_add_f32_e32 v30, v30, v31
	ds_bpermute_b32 v31, v168, v30
	s_waitcnt lgkmcnt(2)
	v_add_f32_e32 v28, v28, v29
	ds_bpermute_b32 v29, v169, v28
	s_waitcnt lgkmcnt(2)
	v_add_f32_e32 v32, v32, v33
	ds_bpermute_b32 v33, v168, v32
	s_waitcnt lgkmcnt(2)
	v_add_f32_e32 v30, v30, v31
	ds_bpermute_b32 v31, v167, v30
	s_waitcnt lgkmcnt(2)
	v_add_f32_e32 v28, v28, v29
	ds_bpermute_b32 v29, v168, v28
	s_waitcnt lgkmcnt(2)
	v_add_f32_e32 v32, v32, v33
	ds_bpermute_b32 v33, v167, v32
	s_waitcnt lgkmcnt(2)
	v_add_f32_e32 v30, v30, v31
	ds_bpermute_b32 v31, v166, v30
	s_waitcnt lgkmcnt(2)
	v_add_f32_e32 v28, v28, v29
	ds_bpermute_b32 v29, v167, v28
	s_waitcnt lgkmcnt(2)
	v_add_f32_e32 v32, v32, v33
	ds_bpermute_b32 v33, v166, v32
	ds_bpermute_b32 v79, v164, v78
	s_waitcnt lgkmcnt(3)
	v_add_f32_e32 v30, v30, v31
	s_waitcnt lgkmcnt(2)
	v_add_f32_e32 v28, v28, v29
	ds_bpermute_b32 v29, v166, v28
	ds_bpermute_b32 v31, v164, v30
	s_waitcnt lgkmcnt(3)
	v_add_f32_e32 v32, v32, v33
	ds_bpermute_b32 v33, v164, v32
	v_add_f32_e32 v58, v76, v77
	s_waitcnt lgkmcnt(2)
	v_add_f32_e32 v28, v28, v29
	ds_bpermute_b32 v29, v164, v28
	v_add_f32_e32 v59, v78, v79
	s_waitcnt lgkmcnt(2)
	v_add_f32_e32 v30, v30, v31
	s_waitcnt lgkmcnt(1)
	v_add_f32_e32 v31, v32, v33
	global_store_dwordx4 v[24:25], v[18:21], off offset:1024
	s_waitcnt lgkmcnt(0)
	v_add_f32_e32 v28, v28, v29
	v_cndmask_b32_e64 v29, v57, v74, s[4:5]
	v_cndmask_b32_e64 v29, v29, v75, s[6:7]
	v_cndmask_b32_e64 v29, v29, v58, s[8:9]
	v_cndmask_b32_e64 v29, v29, v59, s[10:11]
	v_cndmask_b32_e64 v29, v29, v30, s[12:13]
	v_cndmask_b32_e64 v29, v29, v31, s[14:15]
	v_cndmask_b32_e64 v28, v29, v28, s[16:17]
	v_add_f32_e32 v29, v71, v28
	v_mul_f32_e64 v28, |v29|, s29
	v_exp_f32_e32 v78, v28
	v_ldexp_f32 v28, v23, v27
	v_min_f32_e32 v23, 0, v29
	v_add_f32_e32 v20, 1.0, v78
	v_add_f32_e32 v18, -1.0, v20
	v_sub_f32_e32 v19, v18, v20
	v_add_f32_e32 v19, 1.0, v19
	v_sub_f32_e32 v18, v78, v18
	v_add_f32_e32 v21, v18, v19
	v_frexp_mant_f32_e32 v24, v20
	v_cvt_f64_f32_e32 v[18:19], v20
	v_frexp_exp_i32_f64_e32 v18, v[18:19]
	v_cmp_gt_f32_e32 vcc, s37, v24
	s_nop 1
	v_subbrev_co_u32_e32 v57, vcc, 0, v18, vcc
	v_sub_u32_e32 v18, 0, v57
	v_ldexp_f32 v27, v20, v18
	v_ldexp_f32 v29, v21, v18
	v_pk_add_f32 v[18:19], v[26:27], 1.0 op_sel_hi:[1,0]
	v_pk_add_f32 v[32:33], v[26:27], -1.0 op_sel_hi:[1,0]
	v_pk_add_f32 v[20:21], v[18:19], -1.0 op_sel_hi:[1,0]
	v_pk_add_f32 v[58:59], v[32:33], 1.0 op_sel_hi:[1,0]
	v_pk_add_f32 v[20:21], v[26:27], v[20:21] neg_lo:[0,1] neg_hi:[0,1]
	v_pk_add_f32 v[26:27], v[26:27], v[58:59] neg_lo:[0,1] neg_hi:[0,1]
	v_pk_add_f32 v[20:21], v[28:29], v[20:21]
	v_pk_add_f32 v[26:27], v[28:29], v[26:27]
	v_pk_add_f32 v[24:25], v[18:19], v[20:21]
	v_pk_add_f32 v[28:29], v[32:33], v[26:27]
	v_rcp_f32_e32 v30, v24
	v_rcp_f32_e32 v31, v25
	v_pk_add_f32 v[18:19], v[24:25], v[18:19] neg_lo:[0,1] neg_hi:[0,1]
	v_pk_add_f32 v[32:33], v[28:29], v[32:33] neg_lo:[0,1] neg_hi:[0,1]
	v_pk_add_f32 v[18:19], v[20:21], v[18:19] neg_lo:[0,1] neg_hi:[0,1]
	v_pk_mul_f32 v[20:21], v[28:29], v[30:31]
	v_pk_add_f32 v[26:27], v[26:27], v[32:33] neg_lo:[0,1] neg_hi:[0,1]
	v_pk_mul_f32 v[32:33], v[24:25], v[20:21]
	v_cmp_neq_f32_e32 vcc, s46, v55
	v_pk_fma_f32 v[58:59], v[20:21], v[24:25], v[32:33] neg_lo:[0,0,1] neg_hi:[0,0,1]
	s_nop 0
	v_pk_fma_f32 v[58:59], v[20:21], v[18:19], v[58:59]
	s_nop 0
	v_pk_add_f32 v[60:61], v[32:33], v[58:59]
	s_nop 0
	v_pk_add_f32 v[62:63], v[28:29], v[60:61] neg_lo:[0,1] neg_hi:[0,1]
; template <int LO, int HI> __global__ void __launch_bounds__(NWAVES * 64, 2) fox_fwd(Args args) {
;     ...
;             { const float z = mine + bfv; const float ls = fminf(z, 0.f) - log1pf(__expf(-fabsf(z)));
	v_pk_add_f32 v[32:33], v[60:61], v[32:33] neg_lo:[0,1] neg_hi:[0,1]
	v_pk_add_f32 v[28:29], v[28:29], v[62:63] neg_lo:[0,1] neg_hi:[0,1]
	s_nop 0
	v_pk_add_f32 v[28:29], v[28:29], v[60:61] neg_lo:[0,1] neg_hi:[0,1]
	s_nop 0
	v_pk_add_f32 v[26:27], v[26:27], v[28:29]
	v_pk_add_f32 v[28:29], v[32:33], v[58:59] neg_lo:[0,1] neg_hi:[0,1]
	s_nop 0
	v_pk_add_f32 v[26:27], v[28:29], v[26:27]
	s_nop 0
	v_pk_add_f32 v[28:29], v[62:63], v[26:27]
	s_nop 0
	v_pk_mul_f32 v[32:33], v[30:31], v[28:29]
	s_nop 0
	v_pk_mul_f32 v[58:59], v[24:25], v[32:33]
	s_nop 0
	v_pk_fma_f32 v[24:25], v[32:33], v[24:25], v[58:59] neg_lo:[0,0,1] neg_hi:[0,0,1]
	s_nop 0
	v_pk_fma_f32 v[18:19], v[32:33], v[18:19], v[24:25]
	v_pk_add_f32 v[24:25], v[62:63], v[28:29] neg_lo:[0,1] neg_hi:[0,1]
	s_nop 0
	v_pk_add_f32 v[24:25], v[26:27], v[24:25]
	v_pk_add_f32 v[26:27], v[58:59], v[18:19]
	s_nop 0
	v_pk_add_f32 v[60:61], v[28:29], v[26:27] neg_lo:[0,1] neg_hi:[0,1]
	v_pk_add_f32 v[58:59], v[26:27], v[58:59] neg_lo:[0,1] neg_hi:[0,1]
	v_pk_add_f32 v[28:29], v[28:29], v[60:61] neg_lo:[0,1] neg_hi:[0,1]
	v_pk_add_f32 v[18:19], v[58:59], v[18:19] neg_lo:[0,1] neg_hi:[0,1]
	v_pk_add_f32 v[26:27], v[28:29], v[26:27] neg_lo:[0,1] neg_hi:[0,1]
	s_nop 0
	v_pk_add_f32 v[24:25], v[24:25], v[26:27]
	s_nop 0
	v_pk_add_f32 v[18:19], v[18:19], v[24:25]
	v_pk_add_f32 v[24:25], v[20:21], v[32:33]
	v_pk_add_f32 v[18:19], v[60:61], v[18:19]
	v_pk_add_f32 v[20:21], v[24:25], v[20:21] neg_lo:[0,1] neg_hi:[0,1]
	v_pk_mul_f32 v[18:19], v[30:31], v[18:19]
	v_pk_add_f32 v[20:21], v[32:33], v[20:21] neg_lo:[0,1] neg_hi:[0,1]
	v_cvt_f32_i32_e32 v32, v56
	v_pk_add_f32 v[18:19], v[20:21], v[18:19]
	v_cvt_f32_i32_e32 v33, v57
	v_pk_add_f32 v[26:27], v[24:25], v[18:19]
	s_nop 0
	v_pk_add_f32 v[20:21], v[26:27], v[24:25] neg_lo:[0,1] neg_hi:[0,1]
	v_pk_mul_f32 v[28:29], v[26:27], v[26:27]
	v_pk_add_f32 v[18:19], v[18:19], v[20:21] neg_lo:[0,1] neg_hi:[0,1]
	v_mov_b32_e32 v20, 0x3ecc95a3
	v_pk_fma_f32 v[30:31], v[28:29], s[20:21], v[20:21] op_sel_hi:[1,0,0]
	s_mov_b32 s20, 0x3f2aaada
	v_ldexp_f32 v24, v26, 1
	v_pk_fma_f32 v[30:31], v[28:29], v[30:31], s[20:21] op_sel_hi:[1,1,0]
	v_ldexp_f32 v25, v27, 1
	v_pk_mul_f32 v[26:27], v[26:27], v[28:29]
	v_pk_mul_f32 v[28:29], v[32:33], s[36:37] op_sel_hi:[1,0]
	v_pk_mul_f32 v[26:27], v[26:27], v[30:31]
	v_pk_fma_f32 v[58:59], v[32:33], s[36:37], v[28:29] op_sel_hi:[1,0,1] neg_lo:[0,0,1] neg_hi:[0,0,1]
	v_pk_add_f32 v[30:31], v[24:25], v[26:27]
	s_mov_b32 s20, 0xb102e308
	v_pk_add_f32 v[24:25], v[30:31], v[24:25] neg_lo:[0,1] neg_hi:[0,1]
	v_ldexp_f32 v57, v19, 1
	v_pk_fma_f32 v[32:33], v[32:33], s[20:21], v[58:59] op_sel_hi:[1,0,1]
	v_pk_add_f32 v[24:25], v[26:27], v[24:25] neg_lo:[0,1] neg_hi:[0,1]
	v_ldexp_f32 v18, v18, 1
	v_mov_b32_e32 v26, v28
	v_mov_b32_e32 v27, v25
	v_mov_b32_e32 v56, v32
	v_mov_b32_e32 v19, v57
	v_pk_add_f32 v[26:27], v[26:27], v[56:57]
	v_pk_add_f32 v[56:57], v[18:19], v[24:25]
	v_mov_b32_e32 v25, v31
	v_mov_b32_e32 v19, v57
	v_pk_add_f32 v[58:59], v[28:29], v[32:33]
	v_pk_add_f32 v[18:19], v[18:19], v[24:25]
	v_pk_add_f32 v[24:25], v[30:31], v[56:57]
	v_mov_b32_e32 v74, v30
	v_pk_add_f32 v[60:61], v[58:59], v[24:25]
	v_mov_b32_e32 v66, v24
	v_mov_b32_e32 v67, v61
	v_mov_b32_e32 v75, v59
	v_pk_add_f32 v[66:67], v[66:67], v[74:75] neg_lo:[0,1] neg_hi:[0,1]
	v_mov_b32_e32 v62, v60
	v_mov_b32_e32 v63, v59
	v_mov_b32_e32 v64, v58
	v_mov_b32_e32 v65, v29
	v_mov_b32_e32 v74, v58
	v_mov_b32_e32 v75, v61
	v_mov_b32_e32 v29, v67
	v_pk_add_f32 v[62:63], v[62:63], v[64:65] neg_lo:[0,1] neg_hi:[0,1]
	v_mov_b32_e32 v64, v24
	v_mov_b32_e32 v65, v33
	v_pk_add_f32 v[28:29], v[74:75], v[28:29] neg_lo:[0,1] neg_hi:[0,1]
	v_pk_add_f32 v[64:65], v[64:65], v[62:63] neg_lo:[0,1] neg_hi:[0,1]
	v_mov_b32_e32 v74, v28
	v_mov_b32_e32 v75, v63
	v_mov_b32_e32 v76, v60
	v_mov_b32_e32 v77, v25
	v_mov_b32_e32 v63, v31
	v_pk_add_f32 v[74:75], v[32:33], v[74:75] neg_lo:[0,1] neg_hi:[0,1]
	v_pk_add_f32 v[62:63], v[76:77], v[62:63] neg_lo:[0,1] neg_hi:[0,1]
	v_mov_b32_e32 v33, v59
	v_pk_add_f32 v[26:27], v[26:27], v[62:63] neg_lo:[0,1] neg_hi:[0,1]
	v_pk_add_f32 v[28:29], v[32:33], v[28:29] neg_lo:[0,1] neg_hi:[0,1]
	v_pk_add_f32 v[18:19], v[18:19], v[66:67] neg_lo:[0,1] neg_hi:[0,1]
	v_pk_add_f32 v[24:25], v[24:25], v[30:31] neg_lo:[0,1] neg_hi:[0,1]
	v_pk_add_f32 v[30:31], v[18:19], v[28:29]
	v_mov_b32_e32 v29, v65
	v_mov_b32_e32 v19, v27
	v_pk_add_f32 v[32:33], v[64:65], v[26:27]
	v_pk_add_f32 v[18:19], v[28:29], v[18:19]
	v_mov_b32_e32 v26, v30
	v_pk_add_f32 v[18:19], v[18:19], v[74:75] neg_lo:[0,1] neg_hi:[0,1]
	v_mov_b32_e32 v27, v33
; #define GAS __attribute__((address_space(1)))
; #define LAS __attribute__((address_space(3)))
; __device__ __forceinline__ unsigned pk2(float lo, float hi) { return pg8::cvt_pk_bf16(lo, hi); }
; template <int LO, int HI> __global__ void __launch_bounds__(NWAVES * 64, 2) fox_fwd(Args args) {
;     ...
;         const float bfv = b_f[lane & 7]; f32x4 lsq[4];
; #pragma unroll
;         for (int k = 0; k < 4; ++k) lsq[k] = (f32x4){0.f, 0.f, 0.f, 0.f};
;         for (int r = 0; r < 16; ++r) { const int m = m0 + r;
;             const GAS float* xr = (const GAS float*)(x + (size_t)m * D);
;             f32x4 v[4]; float s2 = 0.f;
; #pragma unroll
;             for (int j = 0; j < 4; ++j) { v[j] = *(const GAS f32x4*)(xr + P1COL(j)); s2 += (v[j][0] * v[j][0] + v[j][1] * v[j][1]) + (v[j][2] * v[j][2] + v[j][3] * v[j][3]); }
;             const float rstd = 1.0f / sqrtf(wave_sum(s2) * (1.0f / D) + EPS);
; #pragma unroll
;             for (int j = 0; j < 4; ++j) v[j] = v[j] * rstd * gm[j] + sh[j];
; #pragma unroll
;             for (int j = 0; j < 2; ++j) { v4u o; o.x = pk2(v[2 * j][0], v[2 * j][1]); o.y = pk2(v[2 * j][2], v[2 * j][3]); o.z = pk2(v[2 * j + 1][0], v[2 * j + 1][1]); o.w = pk2(v[2 * j + 1][2], v[2 * j + 1][3]);
;                 *(GAS v4u*)(HB + (size_t)m * D + 8 * lane + 512 * j) = o; }
;             float fl[8];
; #pragma unroll
;             for (int q = 0; q < 8; ++q) { float a = 0.f;
; #pragma unroll
;                 for (int j = 0; j < 4; ++j) { const f32x4 w = *(const LAS f32x4*)(wf + q * 1024 + P1COL(j)); a += (v[j][0] * w[0] + v[j][1] * w[1]) + (v[j][2] * w[2] + v[j][3] * w[3]); }
;                 fl[q] = wave_sum(a); }
;             float mine = fl[0];
; #pragma unroll
;             for (int q = 1; q < 8; ++q) mine = (lane == q) ? fl[q] : mine;
;             { const float z = mine + bfv; const float ls = fminf(z, 0.f) - log1pf(__expf(-fabsf(z)));
	v_pk_add_f32 v[24:25], v[56:57], v[24:25] neg_lo:[0,1] neg_hi:[0,1]
	v_pk_add_f32 v[26:27], v[26:27], v[18:19] neg_lo:[0,1] neg_hi:[0,1]
	v_pk_add_f32 v[18:19], v[24:25], v[18:19] neg_lo:[0,1] neg_hi:[0,1]
	v_pk_add_f32 v[26:27], v[28:29], v[26:27] neg_lo:[0,1] neg_hi:[0,1]
	v_pk_add_f32 v[24:25], v[32:33], v[30:31]
	v_pk_add_f32 v[18:19], v[18:19], v[26:27]
	v_pk_add_f32 v[26:27], v[60:61], v[24:25]
	v_mov_b32_e32 v64, 0x7f800000
	v_pk_add_f32 v[28:29], v[26:27], v[60:61] neg_lo:[0,1] neg_hi:[0,1]
	v_mov_b32_e32 v65, 0x7fc00000
	v_pk_add_f32 v[24:25], v[24:25], v[28:29] neg_lo:[0,1] neg_hi:[0,1]
	v_mov_b32_e32 v66, 0xff800000
	v_pk_add_f32 v[18:19], v[18:19], v[24:25]
	s_add_u32 s20, s26, s34
	v_pk_add_f32 v[18:19], v[26:27], v[18:19]
	s_addc_u32 s21, s27, s35
	v_cndmask_b32_e32 v18, v64, v18, vcc
	v_cmp_neq_f32_e32 vcc, s46, v78
	s_mov_b64 s[34:35], 0x2000
	v_mov_b32_e32 v58, 0x3f317218
	v_cndmask_b32_e32 v19, v64, v19, vcc
	v_cmp_ngt_f32_e32 vcc, -1.0, v78
	v_mov_b32_e32 v21, v37
	v_mov_b32_e32 v30, v37
	v_cndmask_b32_e32 v19, v65, v19, vcc
	v_cmp_ngt_f32_e32 vcc, -1.0, v55
	v_mov_b32_e32 v31, v37
	v_mov_b32_e32 v32, v37
	v_cndmask_b32_e32 v18, v65, v18, vcc
	v_cmp_neq_f32_e32 vcc, -1.0, v55
	v_mov_b32_e32 v33, v37
	v_mov_b32_e32 v26, v37
	v_cndmask_b32_e32 v18, v66, v18, vcc
	v_cmp_neq_f32_e32 vcc, -1.0, v78
	v_mov_b32_e32 v27, v37
	v_mov_b32_e32 v28, v37
	v_cndmask_b32_e32 v19, v66, v19, vcc
	v_cmp_lt_f32_e64 vcc, |v78|, s47
	v_mov_b32_e32 v29, v37
	v_mov_b32_e32 v24, v37
	v_cndmask_b32_e32 v19, v19, v78, vcc
	v_cmp_lt_f32_e64 vcc, |v55|, s47
	v_mov_b32_e32 v25, v37
	s_nop 0
	v_cndmask_b32_e32 v18, v18, v55, vcc
	v_pk_add_f32 v[18:19], v[22:23], v[18:19] neg_lo:[0,1] neg_hi:[0,1]
	v_mov_b32_e32 v55, v37
	v_lshl_add_u64 v[22:23], s[20:21], 0, v[36:37]
	s_mov_b64 s[20:21], 0x2001400
	v_lshl_add_u64 v[54:55], s[30:31], 0, v[54:55]
	v_lshl_add_u64 v[56:57], v[22:23], 0, s[20:21]
	s_mov_b64 s[30:31], 0
	v_mov_b32_e32 v22, v37
	v_mov_b32_e32 v23, v37
	ds_read_b128 v[100:103], v72
	ds_read_b128 v[104:107], v72 offset:16
	ds_read_b128 v[108:111], v72 offset:2048
	ds_read_b128 v[112:115], v72 offset:2064
	ds_read_b128 v[116:119], v72 offset:4096
	ds_read_b128 v[120:123], v72 offset:4112
	ds_read_b128 v[124:127], v72 offset:6144
	ds_read_b128 v[128:131], v72 offset:6160
	ds_read_b128 v[132:135], v72 offset:8192
	ds_read_b128 v[136:139], v72 offset:8208
	ds_read_b128 v[140:143], v72 offset:10240
	ds_read_b128 v[144:147], v72 offset:10256
	s_waitcnt lgkmcnt(0)
	ds_read_b128 v[148:151], v72 offset:12288
	ds_read_b128 v[152:155], v72 offset:12304
	ds_read_b128 v[156:159], v72 offset:14336
	ds_read_b128 v[170:173], v72 offset:14352
	ds_read_b128 v[174:177], v72 offset:16384
	ds_read_b128 v[178:181], v72 offset:16400
	ds_read_b128 v[182:185], v72 offset:18432
	ds_read_b128 v[186:189], v72 offset:18448
	ds_read_b128 v[190:193], v72 offset:20480
	ds_read_b128 v[194:197], v72 offset:20496
	ds_read_b128 v[198:201], v72 offset:22528
	ds_read_b128 v[202:205], v72 offset:22544
	s_waitcnt lgkmcnt(0)
	ds_read_b128 v[206:209], v72 offset:24576
	ds_read_b128 v[210:213], v72 offset:24592
	ds_read_b128 v[226:229], v72 offset:26624
	ds_read_b128 v[230:233], v72 offset:26640
	ds_read_b128 v[234:237], v72 offset:28672
	ds_read_b128 v[238:241], v72 offset:28688
	ds_read_b128 v[242:245], v72 offset:30720
	ds_read_b128 v[246:249], v72 offset:30736
	s_waitcnt lgkmcnt(0)
	s_mov_b32 s52, m0
	s_mov_b32 s62, 0xaaaaaaaa
	s_mov_b32 s63, 0xaaaaaaaa
	s_mov_b32 s64, 0xcccccccc
	s_mov_b32 s65, 0xcccccccc
	s_mov_b32 s66, 0xf0f0f0f0
	s_mov_b32 s67, 0xf0f0f0f0
	s_mov_b64 s[56:57], 0x2000
	s_mov_b64 s[58:59], 16
	s_mov_b64 s[60:61], 0x800
	v_lshrrev_b32_e32 v224, 6, v0
	v_mbcnt_lo_u32_b32 v225, -1, 0
	v_mbcnt_hi_u32_b32 v225, -1, v225
	v_readfirstlane_b32 s50, v224
	v_lshlrev_b32_e32 v224, 4, v225
	s_lshl_b32 s50, s50, 12
	s_add_i32 s50, s50, 0x11000
	s_mov_b32 s53, 0
	v_mov_b32_e32 v160, s53
	v_mov_b32_e32 v161, 0
	v_lshl_add_u64 v[160:161], v[54:55], 0, v[160:161]
	v_lshl_add_u64 v[250:251], v[160:161], 0, s[56:57]
	v_lshl_add_u64 v[252:253], v[160:161], 0, s[34:35]
	v_lshl_add_u64 v[254:255], v[160:161], 0, s[38:39]
	v_lshl_add_u64 v[252:253], v[252:253], 0, s[58:59]
	v_lshl_add_u64 v[254:255], v[254:255], 0, s[58:59]
	v_lshl_add_u64 v[160:161], v[250:251], 0, s[60:61]
	s_mov_b32 m0, s50
	s_nop 0
	global_load_lds_dwordx4 v[250:251], off
	s_add_i32 m0, s50, 0x400
	s_nop 0
	global_load_lds_dwordx4 v[252:253], off
	s_add_i32 m0, s50, 0x800
	s_nop 0
	global_load_lds_dwordx4 v[254:255], off
	s_add_i32 m0, s50, 0xc00
	s_nop 0
	global_load_lds_dwordx4 v[160:161], off

; #define GAS __attribute__((address_space(1)))
; #define LAS __attribute__((address_space(3)))
; __device__ __forceinline__ unsigned pk2(float lo, float hi) { return pg8::cvt_pk_bf16(lo, hi); }
; template <int LO, int HI> __global__ void __launch_bounds__(NWAVES * 64, 2) fox_fwd(Args args) {
;     ...
;         for (int r = 0; r < 16; ++r) { const int m = m0 + r;
;             const GAS float* xr = (const GAS float*)(x + (size_t)m * D);
;             f32x4 v[4]; float s2 = 0.f;
; #pragma unroll
;             for (int j = 0; j < 4; ++j) { v[j] = *(const GAS f32x4*)(xr + P1COL(j)); s2 += (v[j][0] * v[j][0] + v[j][1] * v[j][1]) + (v[j][2] * v[j][2] + v[j][3] * v[j][3]); }
;             const float rstd = 1.0f / sqrtf(wave_sum(s2) * (1.0f / D) + EPS);
; #pragma unroll
;             for (int j = 0; j < 4; ++j) v[j] = v[j] * rstd * gm[j] + sh[j];
; #pragma unroll
;             for (int j = 0; j < 2; ++j) { v4u o; o.x = pk2(v[2 * j][0], v[2 * j][1]); o.y = pk2(v[2 * j][2], v[2 * j][3]); o.z = pk2(v[2 * j + 1][0], v[2 * j + 1][1]); o.w = pk2(v[2 * j + 1][2], v[2 * j + 1][3]);
;                 *(GAS v4u*)(HB + (size_t)m * D + 8 * lane + 512 * j) = o; }
;     ...
;             for (int q = 0; q < 8; ++q) { float a = 0.f;
; #pragma unroll
;                 for (int j = 0; j < 4; ++j) { const f32x4 w = *(const LAS f32x4*)(wf + q * 1024 + P1COL(j)); a += (v[j][0] * w[0] + v[j][1] * w[1]) + (v[j][2] * w[2] + v[j][3] * w[3]); }
.Lp1dma_skip:
	s_cmp_eq_u32 s30, 0
	v_pk_mul_f32 v[86:87], v[62:63], v[62:63]
	v_pk_mul_f32 v[88:89], v[60:61], v[60:61]
	v_pk_mul_f32 v[90:91], v[76:77], v[76:77]
	v_pk_mul_f32 v[92:93], v[74:75], v[74:75]
	v_pk_mov_b32 v[96:97], v[88:89], v[86:87] op_sel:[1,0]
	v_mov_b32_e32 v89, v87
	v_pk_mov_b32 v[86:87], v[92:93], v[90:91] op_sel:[1,0]
	v_mov_b32_e32 v93, v91
	v_mul_f32_e32 v36, v83, v83
	v_mul_f32_e32 v94, v85, v85
	v_pk_add_f32 v[88:89], v[96:97], v[88:89]
	v_pk_add_f32 v[86:87], v[86:87], v[92:93]
	v_mul_f32_e32 v59, v78, v78
	v_mul_f32_e32 v67, v79, v79
	v_mul_f32_e32 v98, v80, v80
	v_mul_f32_e32 v99, v81, v81
	v_pk_fma_f32 v[90:91], v[82:83], v[82:83], v[36:37] op_sel_hi:[1,1,0]
	v_pk_fma_f32 v[94:95], v[84:85], v[84:85], v[94:95] op_sel_hi:[1,1,0]
	v_pk_add_f32 v[88:89], v[88:89], v[88:89] op_sel:[0,1] op_sel_hi:[1,0]
	v_pk_add_f32 v[86:87], v[86:87], v[86:87] op_sel:[0,1] op_sel_hi:[1,0]
	v_mov_b32_e32 v91, v98
	v_mov_b32_e32 v95, v99
	v_mov_b32_e32 v89, v59
	v_mov_b32_e32 v87, v67
	v_pk_add_f32 v[90:91], v[90:91], v[94:95]
	v_pk_add_f32 v[86:87], v[88:89], v[86:87]
	s_nop 0
	v_pk_add_f32 v[86:87], v[86:87], v[90:91]
	s_nop 0
	v_add_f32_e32 v36, v86, v87
	s_waitcnt lgkmcnt(0)
	s_nop 1
	v_add_f32_dpp v59, v36, v36 quad_perm:[1,0,3,2] row_mask:0xf bank_mask:0xf
	s_nop 1
	v_add_f32_dpp v36, v59, v59 quad_perm:[2,3,0,1] row_mask:0xf bank_mask:0xf
	s_nop 1
	v_add_f32_dpp v59, v36, v36 row_half_mirror row_mask:0xf bank_mask:0xf
	s_nop 1
	v_add_f32_dpp v36, v59, v59 row_mirror row_mask:0xf bank_mask:0xf
	v_mov_b32_e32 v59, v36
	s_nop 1
	v_permlane16_swap_b32_e32 v59, v36
	v_add_f32_e32 v59, v59, v36
	v_mov_b32_e32 v36, v59
	s_nop 1
	v_permlane32_swap_b32_e32 v36, v59
	v_add_f32_e32 v36, v36, v59
	v_fmamk_f32 v36, v36, 0x3a800000, v69
	v_mul_f32_e32 v59, 0x4f800000, v36
	v_cmp_gt_f32_e32 vcc, s45, v36
	s_nop 1
	v_cndmask_b32_e32 v36, v36, v59, vcc
	v_sqrt_f32_e32 v59, v36
	s_nop 0
	v_add_u32_e32 v67, -1, v59
	v_add_u32_e32 v86, 1, v59
	v_fma_f32 v87, -v67, v59, v36
	v_fma_f32 v88, -v86, v59, v36
	v_cmp_ge_f32_e64 s[20:21], 0, v87
	s_nop 1
	v_cndmask_b32_e64 v59, v59, v67, s[20:21]
	v_cmp_lt_f32_e64 s[20:21], 0, v88
	s_nop 1
	v_cndmask_b32_e64 v59, v59, v86, s[20:21]
	v_mul_f32_e32 v67, 0x37800000, v59
	v_cndmask_b32_e32 v59, v59, v67, vcc
	v_cmp_class_f32_e32 vcc, v36, v70
	s_nop 1
	v_cndmask_b32_e32 v36, v59, v36, vcc
	v_div_scale_f32 v59, s[20:21], v36, v36, 1.0
	v_rcp_f32_e32 v86, v59
	v_div_scale_f32 v67, vcc, 1.0, v36, 1.0
	v_fma_f32 v87, -v59, v86, 1.0
	v_fmac_f32_e32 v86, v87, v86
	v_mul_f32_e32 v87, v67, v86
	v_fma_f32 v88, -v59, v87, v67
	v_fmac_f32_e32 v87, v88, v86
	v_fma_f32 v59, -v59, v87, v67
	v_div_fmas_f32 v59, v59, v86, v87
	v_div_fixup_f32 v36, v59, v36, 1.0
	v_pk_mul_f32 v[60:61], v[36:37], v[60:61] op_sel_hi:[0,1]
	v_pk_mul_f32 v[62:63], v[36:37], v[62:63] op_sel_hi:[0,1]
	v_pk_mul_f32 v[74:75], v[36:37], v[74:75] op_sel_hi:[0,1]
	v_pk_mul_f32 v[76:77], v[36:37], v[76:77] op_sel_hi:[0,1]
	v_pk_mul_f32 v[82:83], v[36:37], v[82:83] op_sel_hi:[0,1]
	v_pk_mul_f32 v[84:85], v[36:37], v[84:85] op_sel_hi:[0,1]
	v_pk_mul_f32 v[78:79], v[36:37], v[78:79] op_sel_hi:[0,1]
	v_pk_mul_f32 v[80:81], v[36:37], v[80:81] op_sel_hi:[0,1]
	v_pk_fma_f32 v[162:163], v[38:39], v[62:63], v[8:9]
	v_pk_fma_f32 v[214:215], v[40:41], v[60:61], v[6:7]
	v_pk_fma_f32 v[216:217], v[42:43], v[76:77], v[4:5]
	v_pk_fma_f32 v[218:219], v[44:45], v[74:75], v[2:3]
	v_cvt_pk_bf16_f32 v74, v214, v215
	v_cvt_pk_bf16_f32 v75, v162, v163
	v_pk_fma_f32 v[60:61], v[46:47], v[84:85], v[16:17]
	v_cvt_pk_bf16_f32 v76, v218, v219
	v_cvt_pk_bf16_f32 v77, v216, v217
	v_pk_fma_f32 v[62:63], v[48:49], v[82:83], v[14:15]
	v_pk_fma_f32 v[220:221], v[50:51], v[80:81], v[12:13]
	v_pk_fma_f32 v[222:223], v[52:53], v[78:79], v[10:11]
	global_store_dwordx4 v[56:57], v[74:77], off offset:-1024
	s_nop 1
	v_cvt_pk_bf16_f32 v74, v62, v63
	v_cvt_pk_bf16_f32 v75, v60, v61
	v_cvt_pk_bf16_f32 v76, v222, v223
	v_cvt_pk_bf16_f32 v77, v220, v221
	s_nop 0
	global_store_dwordx4 v[56:57], v[74:77], off
	v_mul_f32_e32 v36, v214, v100
	v_mul_f32_e32 v59, v214, v116
	v_mul_f32_e32 v67, v214, v132
	v_mul_f32_e32 v74, v214, v148
	v_mul_f32_e32 v75, v214, v174
	v_mul_f32_e32 v76, v214, v190
	v_mul_f32_e32 v77, v214, v206
	v_mul_f32_e32 v250, v214, v234
	v_fmac_f32_e32 v36, v215, v101
	v_fmac_f32_e32 v59, v215, v117
	v_fmac_f32_e32 v67, v215, v133
	v_fmac_f32_e32 v74, v215, v149
	v_fmac_f32_e32 v75, v215, v175
	v_fmac_f32_e32 v76, v215, v191
	v_fmac_f32_e32 v77, v215, v207
	v_fmac_f32_e32 v250, v215, v235
	v_fmac_f32_e32 v36, v162, v102
	v_fmac_f32_e32 v59, v162, v118
	v_fmac_f32_e32 v67, v162, v134
	v_fmac_f32_e32 v74, v162, v150
	v_fmac_f32_e32 v75, v162, v176
	v_fmac_f32_e32 v76, v162, v192
	v_fmac_f32_e32 v77, v162, v208
	v_fmac_f32_e32 v250, v162, v236
	v_fmac_f32_e32 v36, v163, v103
	v_fmac_f32_e32 v59, v163, v119
	v_fmac_f32_e32 v67, v163, v135
	v_fmac_f32_e32 v74, v163, v151
	v_fmac_f32_e32 v75, v163, v177
	v_fmac_f32_e32 v76, v163, v193
	v_fmac_f32_e32 v77, v163, v209
	v_fmac_f32_e32 v250, v163, v237
	v_fmac_f32_e32 v36, v218, v104
	v_fmac_f32_e32 v59, v218, v120
	v_fmac_f32_e32 v67, v218, v136
	v_fmac_f32_e32 v74, v218, v152
	v_fmac_f32_e32 v75, v218, v178
	v_fmac_f32_e32 v76, v218, v194
	v_fmac_f32_e32 v77, v218, v210
	v_fmac_f32_e32 v250, v218, v238
	v_fmac_f32_e32 v36, v219, v105
	v_fmac_f32_e32 v59, v219, v121
	v_fmac_f32_e32 v67, v219, v137
	v_fmac_f32_e32 v74, v219, v153
	v_fmac_f32_e32 v75, v219, v179
	v_fmac_f32_e32 v76, v219, v195
	v_fmac_f32_e32 v77, v219, v211
	v_fmac_f32_e32 v250, v219, v239
	v_fmac_f32_e32 v36, v216, v106
	v_fmac_f32_e32 v59, v216, v122
; #define LAS __attribute__((address_space(3)))
; template <int LO, int HI> __global__ void __launch_bounds__(NWAVES * 64, 2) fox_fwd(Args args) {
;     ...
;             for (int q = 0; q < 8; ++q) { float a = 0.f;
; #pragma unroll
;                 for (int j = 0; j < 4; ++j) { const f32x4 w = *(const LAS f32x4*)(wf + q * 1024 + P1COL(j)); a += (v[j][0] * w[0] + v[j][1] * w[1]) + (v[j][2] * w[2] + v[j][3] * w[3]); }
;                 fl[q] = wave_sum(a); }
;             float mine = fl[0];
; #pragma unroll
;             for (int q = 1; q < 8; ++q) mine = (lane == q) ? fl[q] : mine;
;             { const float z = mine + bfv; const float ls = fminf(z, 0.f) - log1pf(__expf(-fabsf(z)));
; #pragma unroll
;               for (int k = 0; k < 4; ++k)
; #pragma unroll
;                   for (int e = 0; e < 4; ++e) lsq[k][e] = (r == 4 * k + e) ? ls : lsq[k][e]; }
	v_fmac_f32_e32 v67, v216, v138
	v_fmac_f32_e32 v74, v216, v154
	v_fmac_f32_e32 v75, v216, v180
	v_fmac_f32_e32 v76, v216, v196
	v_fmac_f32_e32 v77, v216, v212
	v_fmac_f32_e32 v250, v216, v240
	v_fmac_f32_e32 v36, v217, v107
	v_fmac_f32_e32 v59, v217, v123
	v_fmac_f32_e32 v67, v217, v139
	v_fmac_f32_e32 v74, v217, v155
	v_fmac_f32_e32 v75, v217, v181
	v_fmac_f32_e32 v76, v217, v197
	v_fmac_f32_e32 v77, v217, v213
	v_fmac_f32_e32 v250, v217, v241
	v_fmac_f32_e32 v36, v62, v108
	v_fmac_f32_e32 v59, v62, v124
	v_fmac_f32_e32 v67, v62, v140
	v_fmac_f32_e32 v74, v62, v156
	v_fmac_f32_e32 v75, v62, v182
	v_fmac_f32_e32 v76, v62, v198
	v_fmac_f32_e32 v77, v62, v226
	v_fmac_f32_e32 v250, v62, v242
	v_fmac_f32_e32 v36, v63, v109
	v_fmac_f32_e32 v59, v63, v125
	v_fmac_f32_e32 v67, v63, v141
	v_fmac_f32_e32 v74, v63, v157
	v_fmac_f32_e32 v75, v63, v183
	v_fmac_f32_e32 v76, v63, v199
	v_fmac_f32_e32 v77, v63, v227
	v_fmac_f32_e32 v250, v63, v243
	v_fmac_f32_e32 v36, v60, v110
	v_fmac_f32_e32 v59, v60, v126
	v_fmac_f32_e32 v67, v60, v142
	v_fmac_f32_e32 v74, v60, v158
	v_fmac_f32_e32 v75, v60, v184
	v_fmac_f32_e32 v76, v60, v200
	v_fmac_f32_e32 v77, v60, v228
	v_fmac_f32_e32 v250, v60, v244
	v_fmac_f32_e32 v36, v61, v111
	v_fmac_f32_e32 v59, v61, v127
	v_fmac_f32_e32 v67, v61, v143
	v_fmac_f32_e32 v74, v61, v159
	v_fmac_f32_e32 v75, v61, v185
	v_fmac_f32_e32 v76, v61, v201
	v_fmac_f32_e32 v77, v61, v229
	v_fmac_f32_e32 v250, v61, v245
	v_fmac_f32_e32 v36, v222, v112
	v_fmac_f32_e32 v59, v222, v128
	v_fmac_f32_e32 v67, v222, v144
	v_fmac_f32_e32 v74, v222, v170
	v_fmac_f32_e32 v75, v222, v186
	v_fmac_f32_e32 v76, v222, v202
	v_fmac_f32_e32 v77, v222, v230
	v_fmac_f32_e32 v250, v222, v246
	v_fmac_f32_e32 v36, v223, v113
	v_fmac_f32_e32 v59, v223, v129
	v_fmac_f32_e32 v67, v223, v145
	v_fmac_f32_e32 v74, v223, v171
	v_fmac_f32_e32 v75, v223, v187
	v_fmac_f32_e32 v76, v223, v203
	v_fmac_f32_e32 v77, v223, v231
	v_fmac_f32_e32 v250, v223, v247
	v_fmac_f32_e32 v36, v220, v114
	v_fmac_f32_e32 v59, v220, v130
	v_fmac_f32_e32 v67, v220, v146
	v_fmac_f32_e32 v74, v220, v172
	v_fmac_f32_e32 v75, v220, v188
	v_fmac_f32_e32 v76, v220, v204
	v_fmac_f32_e32 v77, v220, v232
	v_fmac_f32_e32 v250, v220, v248
	v_fmac_f32_e32 v36, v221, v115
	v_fmac_f32_e32 v59, v221, v131
	v_fmac_f32_e32 v67, v221, v147
	v_fmac_f32_e32 v74, v221, v173
	v_fmac_f32_e32 v75, v221, v189
	v_fmac_f32_e32 v76, v221, v205
	v_fmac_f32_e32 v77, v221, v233
	v_fmac_f32_e32 v250, v221, v249
	v_mov_b32_e32 v60, v250
	v_mov_b32_e32 v61, 0
	s_waitcnt lgkmcnt(0)
	v_add_f32_e32 v60, v60, v61
	v_cndmask_b32_e64 v62, v59, v36, s[62:63]
	v_cndmask_b32_e64 v63, v74, v67, s[62:63]
	v_cndmask_b32_e64 v78, v76, v75, s[62:63]
	v_cndmask_b32_e64 v79, v60, v77, s[62:63]
	v_cndmask_b32_e64 v80, v36, v59, s[62:63]
	v_cndmask_b32_e64 v81, v67, v74, s[62:63]
	v_cndmask_b32_e64 v82, v75, v76, s[62:63]
	v_cndmask_b32_e64 v61, v77, v60, s[62:63]
	v_add_f32_dpp v36, v62, v80 quad_perm:[1,0,3,2] row_mask:0xf bank_mask:0xf
	v_add_f32_dpp v59, v63, v81 quad_perm:[1,0,3,2] row_mask:0xf bank_mask:0xf
	v_add_f32_dpp v67, v78, v82 quad_perm:[1,0,3,2] row_mask:0xf bank_mask:0xf
	v_add_f32_dpp v74, v79, v61 quad_perm:[1,0,3,2] row_mask:0xf bank_mask:0xf
	v_cndmask_b32_e64 v62, v59, v36, s[64:65]
	v_cndmask_b32_e64 v63, v74, v67, s[64:65]
	v_cndmask_b32_e64 v78, v36, v59, s[64:65]
	v_cndmask_b32_e64 v79, v67, v74, s[64:65]
	v_add_f32_dpp v80, v62, v78 quad_perm:[2,3,0,1] row_mask:0xf bank_mask:0xf
	v_add_f32_dpp v81, v63, v79 quad_perm:[2,3,0,1] row_mask:0xf bank_mask:0xf
	v_cndmask_b32_e64 v62, v81, v80, s[66:67]
	v_cndmask_b32_e64 v63, v80, v81, s[66:67]
	s_nop 1
	v_mov_b32_dpp v78, v62 row_shl:4 row_mask:0xf bank_mask:0x5
	v_mov_b32_dpp v78, v62 row_shr:4 row_mask:0xf bank_mask:0xa
	v_add_f32_e32 v79, v63, v78
	s_nop 1
	v_add_f32_dpp v80, v79, v79 row_ror:8 row_mask:0xf bank_mask:0xf
	v_mov_b32_e32 v62, v80
	v_mov_b32_e32 v63, v80
	s_nop 1
	v_permlane16_swap_b32_e32 v62, v63
	v_add_f32_e32 v78, v62, v63
	v_mov_b32_e32 v62, v78
	v_mov_b32_e32 v63, v78
	s_nop 1
	v_permlane32_swap_b32_e32 v62, v63
	v_add_f32_e32 v36, v62, v63
	v_add_f32_e32 v36, v71, v36
	v_min_f32_e32 v67, 0, v36
	v_mul_f32_e64 v36, |v36|, s29
	v_exp_f32_e32 v36, v36
	v_lshl_add_u64 v[56:57], v[56:57], 0, s[40:41]
	v_add_f32_e32 v59, 1.0, v36
	v_add_f32_e32 v62, -1.0, v59
	v_frexp_mant_f32_e32 v63, v59
	v_cvt_f64_f32_e32 v[60:61], v59
	v_sub_f32_e32 v74, v62, v59
	v_frexp_exp_i32_f64_e32 v60, v[60:61]
	v_cmp_gt_f32_e32 vcc, s37, v63
	v_sub_f32_e32 v62, v36, v62
	v_add_f32_e32 v61, 1.0, v74
	v_subbrev_co_u32_e32 v60, vcc, 0, v60, vcc
	v_add_f32_e32 v61, v62, v61
	v_sub_u32_e32 v62, 0, v60
	v_ldexp_f32 v59, v59, v62
	v_ldexp_f32 v61, v61, v62
	v_add_f32_e32 v62, -1.0, v59
	v_add_f32_e32 v74, 1.0, v59
	v_add_f32_e32 v63, 1.0, v62
	v_add_f32_e32 v75, -1.0, v74
	v_sub_f32_e32 v63, v59, v63
	v_sub_f32_e32 v59, v59, v75
	v_add_f32_e32 v59, v61, v59
	v_add_f32_e32 v75, v61, v63
	v_add_f32_e32 v61, v74, v59
	v_rcp_f32_e32 v78, v61
	v_add_f32_e32 v63, v62, v75
	v_sub_f32_e32 v74, v61, v74
	v_sub_f32_e32 v59, v59, v74
	v_mul_f32_e32 v80, v63, v78
	v_mul_f32_e32 v74, v61, v80
	v_fma_f32 v76, v80, v61, -v74
	v_sub_f32_e32 v62, v63, v62
	v_fmac_f32_e32 v76, v80, v59
	v_sub_f32_e32 v79, v75, v62
	v_add_f32_e32 v62, v74, v76
; template <int LO, int HI> __global__ void __launch_bounds__(NWAVES * 64, 2) fox_fwd(Args args) {
;     ...
;             { const float z = mine + bfv; const float ls = fminf(z, 0.f) - log1pf(__expf(-fabsf(z)));
; #pragma unroll
;               for (int k = 0; k < 4; ++k)
; #pragma unroll
;                   for (int e = 0; e < 4; ++e) lsq[k][e] = (r == 4 * k + e) ? ls : lsq[k][e]; }
;         }
;         if (lane < 8) { f32x4* dst = (f32x4*)(LF + (size_t)(b * 8 + lane) * T + (m0 - b * T));
; #pragma unroll
;             for (int k = 0; k < 4; ++k) dst[k] = lsq[k]; }
	v_sub_f32_e32 v75, v63, v62
	v_mov_b32_e32 v77, v62
	v_pk_add_f32 v[62:63], v[62:63], v[74:75] neg_lo:[0,1] neg_hi:[0,1]
	v_cvt_f32_i32_e32 v60, v60
	v_pk_add_f32 v[62:63], v[62:63], v[76:77] neg_lo:[0,1] neg_hi:[0,1]
	v_cmp_neq_f32_e32 vcc, s46, v36
	v_add_f32_e32 v63, v79, v63
	v_add_f32_e32 v62, v62, v63
	v_add_f32_e32 v63, v75, v62
	v_mul_f32_e32 v77, v78, v63
	v_mul_f32_e32 v74, v61, v77
	v_fma_f32 v76, v77, v61, -v74
	v_sub_f32_e32 v75, v75, v63
	v_fmac_f32_e32 v76, v77, v59
	v_add_f32_e32 v79, v62, v75
	v_add_f32_e32 v81, v80, v77
	v_add_f32_e32 v62, v74, v76
	v_sub_f32_e32 v61, v81, v80
	v_sub_f32_e32 v75, v63, v62
	v_sub_f32_e32 v59, v77, v61
	v_mov_b32_e32 v77, v62
	v_pk_add_f32 v[62:63], v[62:63], v[74:75] neg_lo:[0,1] neg_hi:[0,1]
	s_nop 0
	v_pk_add_f32 v[62:63], v[62:63], v[76:77] neg_lo:[0,1] neg_hi:[0,1]
	s_nop 0
	v_add_f32_e32 v61, v79, v63
	v_add_f32_e32 v61, v62, v61
	v_add_f32_e32 v61, v75, v61
	v_mul_f32_e32 v61, v78, v61
	v_add_f32_e32 v59, v59, v61
	v_add_f32_e32 v61, v81, v59
	v_mul_f32_e32 v62, v61, v61
	v_sub_f32_e32 v74, v61, v81
	v_fmamk_f32 v75, v62, 0x3e9b6dac, v20
	v_ldexp_f32 v63, v61, 1
	v_sub_f32_e32 v74, v59, v74
	v_mul_f32_e32 v61, v61, v62
	v_fmaak_f32 v59, v62, v75, 0x3f2aaada
	v_ldexp_f32 v77, v74, 1
	v_pk_mul_f32 v[74:75], v[60:61], v[58:59]
	s_nop 0
	v_fma_f32 v62, v60, s36, -v74
	v_fmac_f32_e32 v62, 0xb102e308, v60
	v_pk_add_f32 v[60:61], v[74:75], v[62:63]
	v_mov_b32_e32 v76, v74
	v_sub_f32_e32 v59, v61, v63
	v_sub_f32_e32 v59, v75, v59
	v_add_f32_e32 v77, v77, v59
	v_pk_add_f32 v[78:79], v[60:61], v[74:75] neg_lo:[0,1] neg_hi:[0,1]
	v_pk_add_f32 v[74:75], v[60:61], v[76:77]
	v_mov_b32_e32 v63, v60
	v_mov_b32_e32 v79, v75
	v_pk_add_f32 v[82:83], v[62:63], v[78:79] neg_lo:[0,1] neg_hi:[0,1]
	v_pk_add_f32 v[62:63], v[62:63], v[78:79]
	v_mov_b32_e32 v81, v60
	v_pk_add_f32 v[78:79], v[62:63], v[60:61] op_sel:[1,0] op_sel_hi:[0,1] neg_lo:[0,1] neg_hi:[0,1]
	v_mov_b32_e32 v80, v77
	v_mov_b32_e32 v76, v75
	v_mov_b32_e32 v77, v63
	v_pk_mov_b32 v[60:61], v[60:61], v[78:79] op_sel:[1,0]
	v_pk_add_f32 v[74:75], v[74:75], v[78:79] op_sel_hi:[1,0] neg_lo:[0,1] neg_hi:[0,1]
	v_pk_add_f32 v[60:61], v[76:77], v[60:61] neg_lo:[0,1] neg_hi:[0,1]
	v_mov_b32_e32 v74, v82
	v_pk_add_f32 v[60:61], v[80:81], v[60:61] neg_lo:[0,1] neg_hi:[0,1]
	v_mov_b32_e32 v83, v63
	v_pk_add_f32 v[74:75], v[74:75], v[60:61]
	s_nop 0
	v_pk_add_f32 v[76:77], v[74:75], v[74:75] op_sel:[0,1] op_sel_hi:[1,0]
	s_nop 0
	v_pk_add_f32 v[62:63], v[62:63], v[76:77] op_sel:[1,0] op_sel_hi:[0,1]
	v_mov_b32_e32 v75, v62
	v_mov_b32_e32 v61, v76
	v_pk_add_f32 v[76:77], v[74:75], v[82:83] neg_lo:[0,1] neg_hi:[0,1]
	s_nop 0
	v_sub_f32_e32 v59, v74, v76
	v_pk_add_f32 v[60:61], v[60:61], v[76:77] neg_lo:[0,1] neg_hi:[0,1]
	v_sub_f32_e32 v59, v82, v59
	v_add_f32_e32 v59, v60, v59
	v_add_f32_e32 v59, v59, v61
	v_add_f32_e32 v59, v62, v59
	v_cndmask_b32_e32 v59, v64, v59, vcc
	v_cmp_ngt_f32_e32 vcc, -1.0, v36
	s_nop 1
	v_cndmask_b32_e32 v59, v65, v59, vcc
	v_cmp_neq_f32_e32 vcc, -1.0, v36
	s_nop 1
	v_cndmask_b32_e32 v59, v66, v59, vcc
	v_cmp_lt_f32_e64 vcc, |v36|, s47
	s_nop 1
	v_cndmask_b32_e32 v36, v59, v36, vcc
	v_sub_f32_e32 v36, v67, v36
	s_cselect_b64 vcc, -1, 0
	s_cmpk_eq_i32 s30, 0x1000
	v_cndmask_b32_e32 v37, v37, v36, vcc
	s_cselect_b64 vcc, -1, 0
	s_cmpk_eq_i32 s30, 0x2000
	v_cndmask_b32_e32 v21, v21, v36, vcc
	s_cselect_b64 vcc, -1, 0
	s_cmpk_eq_i32 s30, 0x3000
	v_cndmask_b32_e32 v30, v30, v36, vcc
	s_cselect_b64 vcc, -1, 0
	s_cmpk_eq_i32 s30, 0x4000
	v_cndmask_b32_e32 v31, v31, v36, vcc
	s_cselect_b64 vcc, -1, 0
	s_cmpk_eq_i32 s30, 0x5000
	v_cndmask_b32_e32 v32, v32, v36, vcc
	s_cselect_b64 vcc, -1, 0
	s_cmpk_eq_i32 s30, 0x6000
	v_cndmask_b32_e32 v33, v33, v36, vcc
	s_cselect_b64 vcc, -1, 0
	s_cmpk_eq_i32 s30, 0x7000
	v_cndmask_b32_e32 v26, v26, v36, vcc
	s_cselect_b64 vcc, -1, 0
	s_cmpk_eq_u32 s30, 0x8000
	v_cndmask_b32_e32 v27, v27, v36, vcc
	s_cselect_b64 vcc, -1, 0
	s_cmpk_eq_u32 s30, 0x9000
	v_cndmask_b32_e32 v28, v28, v36, vcc
	s_cselect_b64 vcc, -1, 0
	s_cmpk_eq_u32 s30, 0xa000
	v_cndmask_b32_e32 v29, v29, v36, vcc
	s_cselect_b64 vcc, -1, 0
	s_cmpk_eq_u32 s30, 0xb000
	v_cndmask_b32_e32 v22, v22, v36, vcc
	s_cselect_b64 vcc, -1, 0
	s_cmpk_eq_u32 s30, 0xc000
	v_cndmask_b32_e32 v23, v23, v36, vcc
	s_cselect_b64 vcc, -1, 0
	s_cmpk_eq_u32 s30, 0xd000
	v_cndmask_b32_e32 v24, v24, v36, vcc
	s_cselect_b64 vcc, -1, 0
	s_add_u32 s30, s30, 0x1000
	s_addc_u32 s31, s31, 0
	s_cmpk_eq_u32 s30, 0xe000
	v_cndmask_b32_e32 v25, v25, v36, vcc
	s_cbranch_scc0 .LBB0_131
	s_mov_b32 m0, s52
	v_cmp_gt_u32_e32 vcc, 8, v1
	s_and_saveexec_b64 s[4:5], vcc
	s_cbranch_execz .LBB0_134
	v_lshl_or_b32 v2, s44, 3, v1
	v_ashrrev_i32_e32 v3, 31, v2
	s_lshl_b32 s6, s44, 12
	v_lshlrev_b64 v[2:3], 14, v[2:3]
	s_sub_i32 s6, s28, s6
	v_lshl_add_u64 v[2:3], s[26:27], 0, v[2:3]
	s_ashr_i32 s7, s6, 31
	v_lshl_add_u64 v[2:3], s[6:7], 2, v[2:3]
	s_mov_b64 s[6:7], 0x100000
	v_lshl_add_u64 v[4:5], v[2:3], 0, s[6:7]
	v_add_co_u32_e32 v2, vcc, 0x100000, v2
	v_mov_b32_e32 v20, v37
	s_nop 0
	v_addc_co_u32_e32 v3, vcc, 0, v3, vcc
	global_store_dwordx4 v[2:3], v[18:21], off
	global_store_dwordx4 v[4:5], v[30:33], off offset:16
	global_store_dwordx4 v[4:5], v[26:29], off offset:32
	global_store_dwordx4 v[4:5], v[22:25], off offset:48
